# bf16 GEMM epilogues (LRU_IN, ML_IN, R7_IN): permlane16 swap pairs 16-col pieces into 16-byte stores, scalar tile base; LRU_OUT last layer skips unused ctx tiles
# speedup vs baseline: 1.2188x; 1.0155x over previous
; #define PG8_STAGE(bufoff, gbase, voff) do { _Pragma("unroll") for (int _i = 0; _i < 2; ++_i) \
;     __builtin_amdgcn_global_load_lds((const unsigned*)((const char*)(gbase) + (voff)[_i]), (PG8_LAS unsigned*)(lds + (bufoff) + ldsw + _i * 8192), 16, 0, 0); } while (0)
; #define PG8_LDA(dst, b, h) do { _Pragma("unroll") for (int m = 0; m < 4; ++m) _Pragma("unroll") for (int k = 0; k < 2; ++k) dst[m][k] = *(const PG8_LAS bf16x8*)(lds + PG8_SA(b, h) + aoff + m * 2048 + k * 1024); } while (0)
; #define PG8_LDB(dst, b, h) do { _Pragma("unroll") for (int n = 0; n < 2; ++n) _Pragma("unroll") for (int k = 0; k < 2; ++k) dst[n][k] = *(const PG8_LAS bf16x8*)(lds + PG8_SB(b, h) + boff + n * 2048 + k * 1024); } while (0)
; #define PG8_MMA(ai, bj, At, Bt) do { __builtin_amdgcn_s_setprio(1); _Pragma("unroll") for (int m = 0; m < 4; ++m) _Pragma("unroll") for (int n = 0; n < 2; ++n) _Pragma("unroll") for (int k = 0; k < 2; ++k) \
;     acc[ai][bj][m][n] = __builtin_amdgcn_mfma_f32_16x16x32_bf16(Bt[n][k], At[m][k], acc[ai][bj][m][n], 0, 0, 0); __builtin_amdgcn_s_setprio(0); } while (0)
; #define PG8_WAIT_L(n) asm volatile("s_waitcnt lgkmcnt(" #n ")" ::: "memory")
; #define PG8_BAR __builtin_amdgcn_s_barrier()
; #define PG8_SCHED __builtin_amdgcn_sched_barrier(0)
; template <class Epi>
; __device__ __forceinline__ void gemm_phase(PG8_LAS unsigned char* lds, const Gemm g, const StaticOrder& S, const Epi& E) {
;     ...
;     for (int t = 0; t < nt; t += 2) {
;       const bool last = (t == nt - 2);
;       const char* a1 = cA + (size_t)(t + 1) * kstep;
;       const char* a2 = last ? nA : cA + (size_t)(t + 2) * kstep; const char* b2 = last ? nB : cB + (size_t)(t + 2) * kstep;
;       const char* a3 = a2 + kstep; const char* b3 = b2 + kstep;
;       PG8_LDB(B0, 0, 0); PG8_SCHED; PG8_LDA(At, 0, 0); PG8_STAGE(PG8_SA(1, 1), a1 + hstep, voffA);
;       PG8_WAIT_L(8); PG8_BAR; PG8_WAIT_L(0); PG8_MMA(0, 0, At, B0); PG8_BAR; PG8_SCHED;
;       PG8_LDB(B1, 0, 1); PG8_STAGE(PG8_SB(0, 0), b2, voffB);
;       PG8_BAR; PG8_WAIT_L(0); PG8_MMA(0, 1, At, B1); PG8_BAR;
;       PG8_LDA(At, 0, 1); PG8_STAGE(PG8_SA(0, 0), a2, voffA);
;       PG8_BAR; PG8_WAIT_L(0); PG8_MMA(1, 0, At, B0); PG8_BAR; PG8_SCHED;
;       PG8_STAGE(PG8_SB(0, 1), b2 + hstep, voffB);
.LBB0_294:
	s_add_u32 s42, s10, 0xfff80080
	s_addc_u32 s43, s11, -1
	s_add_i32 s51, 0, 0x10000
	v_add_u32_e32 v0, s51, v166
	ds_read_b128 v[158:161], v0
	ds_read_b128 v[162:165], v0 offset:1024
	ds_read_b128 v[188:191], v0 offset:2048
	ds_read_b128 v[192:195], v0 offset:3072
	s_cmp_eq_u32 s49, 28
	s_cselect_b32 s45, s7, s43
	s_cselect_b32 s44, s9, s42
	s_cselect_b32 s43, s31, s48
	s_cselect_b32 s42, s46, s47
	v_lshl_add_u64 v[178:179], s[10:11], 0, v[154:155]
	s_add_i32 m0, s58, 0xc000
	ds_read_b128 v[196:199], v167
	ds_read_b128 v[200:203], v167 offset:1024
	ds_read_b128 v[204:207], v167 offset:2048
	ds_read_b128 v[208:211], v167 offset:3072
	ds_read_b128 v[212:215], v167 offset:4096
	ds_read_b128 v[216:219], v167 offset:5120
	ds_read_b128 v[220:223], v167 offset:6144
	ds_read_b128 v[224:227], v167 offset:7168
	global_load_lds_dwordx4 v[178:179], off
	v_lshl_add_u64 v[178:179], s[10:11], 0, v[156:157]
	s_add_i32 m0, s58, 0xe000
	s_nop 0
	global_load_lds_dwordx4 v[178:179], off
	s_waitcnt lgkmcnt(8)
	s_barrier
	s_waitcnt lgkmcnt(0)
	s_setprio 1
	s_waitcnt lgkmcnt(0)
	v_mfma_f32_16x16x32_bf16 v[126:129], v[158:161], v[196:199], v[126:129]
	v_mfma_f32_16x16x32_bf16 v[122:125], v[188:191], v[196:199], v[122:125]
	v_mfma_f32_16x16x32_bf16 v[110:113], v[158:161], v[204:207], v[110:113]
	v_mfma_f32_16x16x32_bf16 v[106:109], v[188:191], v[204:207], v[106:109]
	v_mfma_f32_16x16x32_bf16 v[94:97], v[158:161], v[212:215], v[94:97]
	v_mfma_f32_16x16x32_bf16 v[90:93], v[188:191], v[212:215], v[90:93]
	v_mfma_f32_16x16x32_bf16 v[78:81], v[158:161], v[220:223], v[78:81]
	v_mfma_f32_16x16x32_bf16 v[74:77], v[188:191], v[220:223], v[74:77]
	v_mfma_f32_16x16x32_bf16 v[126:129], v[162:165], v[200:203], v[126:129]
	v_mfma_f32_16x16x32_bf16 v[122:125], v[192:195], v[200:203], v[122:125]
	v_mfma_f32_16x16x32_bf16 v[110:113], v[162:165], v[208:211], v[110:113]
	v_mfma_f32_16x16x32_bf16 v[106:109], v[192:195], v[208:211], v[106:109]
	v_mfma_f32_16x16x32_bf16 v[94:97], v[162:165], v[216:219], v[94:97]
	v_mfma_f32_16x16x32_bf16 v[90:93], v[192:195], v[216:219], v[90:93]
	v_mfma_f32_16x16x32_bf16 v[78:81], v[162:165], v[224:227], v[78:81]
	v_mfma_f32_16x16x32_bf16 v[74:77], v[192:195], v[224:227], v[74:77]
	s_setprio 0
	s_barrier
	s_add_i32 s66, 0, 0x14000
	s_add_i32 s51, s51, s28
	v_add_u32_e32 v0, s66, v166
	v_lshl_add_u64 v[178:179], s[42:43], 0, v[148:149]
	s_mov_b32 m0, s51
	ds_read_b128 v[228:231], v0
	ds_read_b128 v[232:235], v0 offset:1024
	ds_read_b128 v[236:239], v0 offset:2048
	ds_read_b128 v[240:243], v0 offset:3072
	global_load_lds_dwordx4 v[178:179], off
	v_lshl_add_u64 v[244:245], s[42:43], 0, v[150:151]
	s_add_i32 m0, s51, 0x2000
	s_nop 0
	global_load_lds_dwordx4 v[244:245], off
	s_barrier
	s_waitcnt lgkmcnt(0)
	s_setprio 1
	s_waitcnt lgkmcnt(0)
	v_mfma_f32_16x16x32_bf16 v[118:121], v[228:231], v[196:199], v[118:121]
	v_mfma_f32_16x16x32_bf16 v[114:117], v[236:239], v[196:199], v[114:117]
	v_mfma_f32_16x16x32_bf16 v[102:105], v[228:231], v[204:207], v[102:105]
	v_mfma_f32_16x16x32_bf16 v[98:101], v[236:239], v[204:207], v[98:101]
	v_mfma_f32_16x16x32_bf16 v[86:89], v[228:231], v[212:215], v[86:89]
	v_mfma_f32_16x16x32_bf16 v[82:85], v[236:239], v[212:215], v[82:85]
	v_mfma_f32_16x16x32_bf16 v[70:73], v[228:231], v[220:223], v[70:73]
	v_mfma_f32_16x16x32_bf16 v[66:69], v[236:239], v[220:223], v[66:69]
	v_mfma_f32_16x16x32_bf16 v[118:121], v[232:235], v[200:203], v[118:121]
	v_mfma_f32_16x16x32_bf16 v[114:117], v[240:243], v[200:203], v[114:117]
	v_mfma_f32_16x16x32_bf16 v[102:105], v[232:235], v[208:211], v[102:105]
	v_mfma_f32_16x16x32_bf16 v[98:101], v[240:243], v[208:211], v[98:101]
	v_mfma_f32_16x16x32_bf16 v[86:89], v[232:235], v[216:219], v[86:89]
	v_mfma_f32_16x16x32_bf16 v[82:85], v[240:243], v[216:219], v[82:85]
	v_mfma_f32_16x16x32_bf16 v[70:73], v[232:235], v[224:227], v[70:73]
	v_mfma_f32_16x16x32_bf16 v[66:69], v[240:243], v[224:227], v[66:69]
	s_setprio 0
	s_mov_b32 m0, s58
	v_lshl_add_u64 v[246:247], s[44:45], 0, v[148:149]
	s_barrier
	ds_read_b128 v[196:199], v167 offset:16384
	ds_read_b128 v[200:203], v167 offset:17408
	ds_read_b128 v[204:207], v167 offset:18432
	ds_read_b128 v[208:211], v167 offset:19456
	ds_read_b128 v[212:215], v167 offset:20480
	ds_read_b128 v[216:219], v167 offset:21504
	ds_read_b128 v[220:223], v167 offset:22528
	ds_read_b128 v[224:227], v167 offset:23552
	global_load_lds_dwordx4 v[246:247], off
	v_lshl_add_u64 v[248:249], s[44:45], 0, v[150:151]
	s_mov_b32 m0, s59
	s_nop 0
	global_load_lds_dwordx4 v[248:249], off
	s_barrier
	s_waitcnt lgkmcnt(0)
	s_setprio 1
	s_waitcnt lgkmcnt(0)
	v_mfma_f32_16x16x32_bf16 v[62:65], v[158:161], v[196:199], v[62:65]
	v_mfma_f32_16x16x32_bf16 v[58:61], v[188:191], v[196:199], v[58:61]
	v_mfma_f32_16x16x32_bf16 v[46:49], v[158:161], v[204:207], v[46:49]
	v_mfma_f32_16x16x32_bf16 v[42:45], v[188:191], v[204:207], v[42:45]
	v_mfma_f32_16x16x32_bf16 v[30:33], v[158:161], v[212:215], v[30:33]
	v_mfma_f32_16x16x32_bf16 v[26:29], v[188:191], v[212:215], v[26:29]
	v_mfma_f32_16x16x32_bf16 v[14:17], v[158:161], v[220:223], v[14:17]
	v_mfma_f32_16x16x32_bf16 v[10:13], v[188:191], v[220:223], v[10:13]
	v_mfma_f32_16x16x32_bf16 v[62:65], v[162:165], v[200:203], v[62:65]
	v_mfma_f32_16x16x32_bf16 v[58:61], v[192:195], v[200:203], v[58:61]
	v_mfma_f32_16x16x32_bf16 v[46:49], v[162:165], v[208:211], v[46:49]
	v_mfma_f32_16x16x32_bf16 v[42:45], v[192:195], v[208:211], v[42:45]
	v_mfma_f32_16x16x32_bf16 v[30:33], v[162:165], v[216:219], v[30:33]
	v_mfma_f32_16x16x32_bf16 v[26:29], v[192:195], v[216:219], v[26:29]
	v_mfma_f32_16x16x32_bf16 v[14:17], v[162:165], v[224:227], v[14:17]
	v_mfma_f32_16x16x32_bf16 v[10:13], v[192:195], v[224:227], v[10:13]
	s_setprio 0
	s_barrier
; #define PG8_STAGE(bufoff, gbase, voff) do { _Pragma("unroll") for (int _i = 0; _i < 2; ++_i) \
;     __builtin_amdgcn_global_load_lds((const unsigned*)((const char*)(gbase) + (voff)[_i]), (PG8_LAS unsigned*)(lds + (bufoff) + ldsw + _i * 8192), 16, 0, 0); } while (0)
; #define PG8_LDA(dst, b, h) do { _Pragma("unroll") for (int m = 0; m < 4; ++m) _Pragma("unroll") for (int k = 0; k < 2; ++k) dst[m][k] = *(const PG8_LAS bf16x8*)(lds + PG8_SA(b, h) + aoff + m * 2048 + k * 1024); } while (0)
; #define PG8_LDB(dst, b, h) do { _Pragma("unroll") for (int n = 0; n < 2; ++n) _Pragma("unroll") for (int k = 0; k < 2; ++k) dst[n][k] = *(const PG8_LAS bf16x8*)(lds + PG8_SB(b, h) + boff + n * 2048 + k * 1024); } while (0)
; #define PG8_MMA(ai, bj, At, Bt) do { __builtin_amdgcn_s_setprio(1); _Pragma("unroll") for (int m = 0; m < 4; ++m) _Pragma("unroll") for (int n = 0; n < 2; ++n) _Pragma("unroll") for (int k = 0; k < 2; ++k) \
;     acc[ai][bj][m][n] = __builtin_amdgcn_mfma_f32_16x16x32_bf16(Bt[n][k], At[m][k], acc[ai][bj][m][n], 0, 0, 0); __builtin_amdgcn_s_setprio(0); } while (0)
; #define PG8_WAIT_V(n) asm volatile("s_waitcnt vmcnt(" #n ")" ::: "memory")
; #define PG8_WAIT_L(n) asm volatile("s_waitcnt lgkmcnt(" #n ")" ::: "memory")
; #define PG8_BAR __builtin_amdgcn_s_barrier()
; #define PG8_SCHED __builtin_amdgcn_sched_barrier(0)
; template <class Epi>
; __device__ __forceinline__ void gemm_phase(PG8_LAS unsigned char* lds, const Gemm g, const StaticOrder& S, const Epi& E) {
;     ...
;       PG8_STAGE(PG8_SB(0, 1), b2 + hstep, voffB);
;       PG8_WAIT_V(6); PG8_BAR; PG8_MMA(1, 1, At, B1); PG8_BAR;
;       PG8_LDB(B0, 1, 0); PG8_SCHED; PG8_LDA(At, 1, 0); PG8_STAGE(PG8_SA(0, 1), a2 + hstep, voffA);
;       PG8_WAIT_L(8); PG8_BAR; PG8_WAIT_L(0); PG8_MMA(0, 0, At, B0); PG8_BAR; PG8_SCHED;
;       PG8_LDB(B1, 1, 1); PG8_STAGE(PG8_SB(1, 0), b3, voffB);
;       PG8_BAR; PG8_WAIT_L(0); PG8_MMA(0, 1, At, B1); PG8_BAR;
;       PG8_LDA(At, 1, 1); PG8_STAGE(PG8_SA(1, 0), a3, voffA);
;       PG8_BAR; PG8_WAIT_L(0); PG8_MMA(1, 0, At, B0); PG8_BAR; PG8_SCHED;
	s_add_u32 s56, s42, 0x80000
	s_addc_u32 s57, s43, 0
	s_add_i32 s51, s66, s28
	v_lshl_add_u64 v[158:159], s[56:57], 0, v[148:149]
	s_mov_b32 m0, s51
	s_nop 0
	global_load_lds_dwordx4 v[158:159], off
	v_lshl_add_u64 v[158:159], s[56:57], 0, v[150:151]
	s_add_i32 m0, s51, 0x2000
	s_nop 0
	global_load_lds_dwordx4 v[158:159], off
	s_waitcnt vmcnt(6)
	s_barrier
	s_setprio 1
	v_mfma_f32_16x16x32_bf16 v[54:57], v[228:231], v[196:199], v[54:57]
	v_mfma_f32_16x16x32_bf16 v[50:53], v[236:239], v[196:199], v[50:53]
	v_mfma_f32_16x16x32_bf16 v[38:41], v[228:231], v[204:207], v[38:41]
	v_mfma_f32_16x16x32_bf16 v[34:37], v[236:239], v[204:207], v[34:37]
	v_mfma_f32_16x16x32_bf16 v[22:25], v[228:231], v[212:215], v[22:25]
	v_mfma_f32_16x16x32_bf16 v[18:21], v[236:239], v[212:215], v[18:21]
	v_mfma_f32_16x16x32_bf16 v[6:9], v[228:231], v[220:223], v[6:9]
	v_mfma_f32_16x16x32_bf16 v[2:5], v[236:239], v[220:223], v[2:5]
	v_mfma_f32_16x16x32_bf16 v[54:57], v[232:235], v[200:203], v[54:57]
	v_mfma_f32_16x16x32_bf16 v[50:53], v[240:243], v[200:203], v[50:53]
	v_mfma_f32_16x16x32_bf16 v[38:41], v[232:235], v[208:211], v[38:41]
	v_mfma_f32_16x16x32_bf16 v[34:37], v[240:243], v[208:211], v[34:37]
	v_mfma_f32_16x16x32_bf16 v[22:25], v[232:235], v[216:219], v[22:25]
	v_mfma_f32_16x16x32_bf16 v[18:21], v[240:243], v[216:219], v[18:21]
	v_mfma_f32_16x16x32_bf16 v[6:9], v[232:235], v[224:227], v[6:9]
	v_mfma_f32_16x16x32_bf16 v[2:5], v[240:243], v[224:227], v[2:5]
	s_setprio 0
	s_add_i32 s51, 0, 0x18000
	v_add_u32_e32 v0, s51, v166
	s_barrier
	ds_read_b128 v[158:161], v0
	ds_read_b128 v[162:165], v0 offset:1024
	ds_read_b128 v[188:191], v0 offset:2048
	ds_read_b128 v[192:195], v0 offset:3072
	s_add_u32 s44, s44, 0x80000
	s_addc_u32 s45, s45, 0
	s_mov_b32 m0, s60
	v_lshl_add_u64 v[228:229], s[44:45], 0, v[148:149]
	ds_read_b128 v[196:199], v167 offset:32768
	ds_read_b128 v[200:203], v167 offset:33792
	ds_read_b128 v[204:207], v167 offset:34816
	ds_read_b128 v[208:211], v167 offset:35840
	ds_read_b128 v[212:215], v167 offset:36864
	ds_read_b128 v[216:219], v167 offset:37888
	ds_read_b128 v[220:223], v167 offset:38912
	ds_read_b128 v[224:227], v167 offset:39936
	global_load_lds_dwordx4 v[228:229], off
	v_lshl_add_u64 v[228:229], s[44:45], 0, v[150:151]
	s_mov_b32 m0, s61
	s_nop 0
	global_load_lds_dwordx4 v[228:229], off
	s_waitcnt lgkmcnt(8)
	s_barrier
	s_waitcnt lgkmcnt(0)
	s_setprio 1
	s_waitcnt lgkmcnt(0)
	v_mfma_f32_16x16x32_bf16 v[126:129], v[158:161], v[196:199], v[126:129]
	v_mfma_f32_16x16x32_bf16 v[122:125], v[188:191], v[196:199], v[122:125]
	v_mfma_f32_16x16x32_bf16 v[110:113], v[158:161], v[204:207], v[110:113]
	v_mfma_f32_16x16x32_bf16 v[106:109], v[188:191], v[204:207], v[106:109]
	v_mfma_f32_16x16x32_bf16 v[94:97], v[158:161], v[212:215], v[94:97]
	v_mfma_f32_16x16x32_bf16 v[90:93], v[188:191], v[212:215], v[90:93]
	v_mfma_f32_16x16x32_bf16 v[78:81], v[158:161], v[220:223], v[78:81]
	v_mfma_f32_16x16x32_bf16 v[74:77], v[188:191], v[220:223], v[74:77]
	v_mfma_f32_16x16x32_bf16 v[126:129], v[162:165], v[200:203], v[126:129]
	v_mfma_f32_16x16x32_bf16 v[122:125], v[192:195], v[200:203], v[122:125]
	v_mfma_f32_16x16x32_bf16 v[110:113], v[162:165], v[208:211], v[110:113]
	v_mfma_f32_16x16x32_bf16 v[106:109], v[192:195], v[208:211], v[106:109]
	v_mfma_f32_16x16x32_bf16 v[94:97], v[162:165], v[216:219], v[94:97]
	v_mfma_f32_16x16x32_bf16 v[90:93], v[192:195], v[216:219], v[90:93]
	v_mfma_f32_16x16x32_bf16 v[78:81], v[162:165], v[224:227], v[78:81]
	v_mfma_f32_16x16x32_bf16 v[74:77], v[192:195], v[224:227], v[74:77]
	s_setprio 0
	s_barrier
	s_add_i32 s44, 0, 0x1c000
	s_add_i32 s45, s51, s28
	v_add_u32_e32 v0, s44, v166
	v_lshl_add_u64 v[178:179], v[178:179], 0, s[4:5]
	s_mov_b32 m0, s45
	ds_read_b128 v[228:231], v0
	ds_read_b128 v[232:235], v0 offset:1024
	ds_read_b128 v[236:239], v0 offset:2048
	ds_read_b128 v[240:243], v0 offset:3072
	global_load_lds_dwordx4 v[178:179], off
	v_lshl_add_u64 v[178:179], v[244:245], 0, s[4:5]
	s_add_i32 m0, s45, 0x2000
	s_nop 0
	global_load_lds_dwordx4 v[178:179], off
	s_barrier
	s_waitcnt lgkmcnt(0)
	s_setprio 1
	s_waitcnt lgkmcnt(0)
	v_mfma_f32_16x16x32_bf16 v[118:121], v[228:231], v[196:199], v[118:121]
	v_mfma_f32_16x16x32_bf16 v[114:117], v[236:239], v[196:199], v[114:117]
	v_mfma_f32_16x16x32_bf16 v[102:105], v[228:231], v[204:207], v[102:105]
	v_mfma_f32_16x16x32_bf16 v[98:101], v[236:239], v[204:207], v[98:101]
	v_mfma_f32_16x16x32_bf16 v[86:89], v[228:231], v[212:215], v[86:89]
	v_mfma_f32_16x16x32_bf16 v[82:85], v[236:239], v[212:215], v[82:85]
	v_mfma_f32_16x16x32_bf16 v[70:73], v[228:231], v[220:223], v[70:73]
	v_mfma_f32_16x16x32_bf16 v[66:69], v[236:239], v[220:223], v[66:69]
	v_mfma_f32_16x16x32_bf16 v[118:121], v[232:235], v[200:203], v[118:121]
	v_mfma_f32_16x16x32_bf16 v[114:117], v[240:243], v[200:203], v[114:117]
	v_mfma_f32_16x16x32_bf16 v[102:105], v[232:235], v[208:211], v[102:105]
	v_mfma_f32_16x16x32_bf16 v[98:101], v[240:243], v[208:211], v[98:101]
	v_mfma_f32_16x16x32_bf16 v[86:89], v[232:235], v[216:219], v[86:89]
	v_mfma_f32_16x16x32_bf16 v[82:85], v[240:243], v[216:219], v[82:85]
	v_mfma_f32_16x16x32_bf16 v[70:73], v[232:235], v[224:227], v[70:73]
	v_mfma_f32_16x16x32_bf16 v[66:69], v[240:243], v[224:227], v[66:69]
	s_setprio 0
	s_mov_b32 m0, s63
	v_lshl_add_u64 v[178:179], v[246:247], 0, s[4:5]
	s_barrier
	ds_read_b128 v[196:199], v167 offset:49152
	ds_read_b128 v[200:203], v167 offset:50176
	ds_read_b128 v[204:207], v167 offset:51200
	ds_read_b128 v[208:211], v167 offset:52224
	ds_read_b128 v[212:215], v167 offset:53248
	ds_read_b128 v[216:219], v167 offset:54272
	ds_read_b128 v[220:223], v167 offset:55296
	ds_read_b128 v[224:227], v167 offset:56320
	global_load_lds_dwordx4 v[178:179], off
	v_lshl_add_u64 v[178:179], v[248:249], 0, s[4:5]
	s_mov_b32 m0, s64
	s_nop 0
	global_load_lds_dwordx4 v[178:179], off
	s_barrier
; #define PG8_STAGE(bufoff, gbase, voff) do { _Pragma("unroll") for (int _i = 0; _i < 2; ++_i) \
;     __builtin_amdgcn_global_load_lds((const unsigned*)((const char*)(gbase) + (voff)[_i]), (PG8_LAS unsigned*)(lds + (bufoff) + ldsw + _i * 8192), 16, 0, 0); } while (0)
; #define PG8_MMA(ai, bj, At, Bt) do { __builtin_amdgcn_s_setprio(1); _Pragma("unroll") for (int m = 0; m < 4; ++m) _Pragma("unroll") for (int n = 0; n < 2; ++n) _Pragma("unroll") for (int k = 0; k < 2; ++k) \
;     acc[ai][bj][m][n] = __builtin_amdgcn_mfma_f32_16x16x32_bf16(Bt[n][k], At[m][k], acc[ai][bj][m][n], 0, 0, 0); __builtin_amdgcn_s_setprio(0); } while (0)
; #define PG8_WAIT_V(n) asm volatile("s_waitcnt vmcnt(" #n ")" ::: "memory")
; #define PG8_WAIT_L(n) asm volatile("s_waitcnt lgkmcnt(" #n ")" ::: "memory")
; #define PG8_BAR __builtin_amdgcn_s_barrier()
; #define PG8_SCHED __builtin_amdgcn_sched_barrier(0)
; template <class Epi>
; __device__ __forceinline__ void gemm_phase(PG8_LAS unsigned char* lds, const Gemm g, const StaticOrder& S, const Epi& E) {
;     ...
;       PG8_BAR; PG8_WAIT_L(0); PG8_MMA(1, 0, At, B0); PG8_BAR; PG8_SCHED;
;       PG8_STAGE(PG8_SB(1, 1), b3 + hstep, voffB);
;       PG8_WAIT_V(6); PG8_BAR; PG8_MMA(1, 1, At, B1); PG8_BAR;
;     }
;     E(acc, cur, wr, wc, fr, fq);
	s_waitcnt lgkmcnt(0)
	s_setprio 1
	s_waitcnt lgkmcnt(0)
	v_mfma_f32_16x16x32_bf16 v[62:65], v[158:161], v[196:199], v[62:65]
	v_mfma_f32_16x16x32_bf16 v[58:61], v[188:191], v[196:199], v[58:61]
	v_mfma_f32_16x16x32_bf16 v[46:49], v[158:161], v[204:207], v[46:49]
	v_mfma_f32_16x16x32_bf16 v[42:45], v[188:191], v[204:207], v[42:45]
	v_mfma_f32_16x16x32_bf16 v[30:33], v[158:161], v[212:215], v[30:33]
	v_mfma_f32_16x16x32_bf16 v[26:29], v[188:191], v[212:215], v[26:29]
	v_mfma_f32_16x16x32_bf16 v[14:17], v[158:161], v[220:223], v[14:17]
	v_mfma_f32_16x16x32_bf16 v[10:13], v[188:191], v[220:223], v[10:13]
	v_mfma_f32_16x16x32_bf16 v[62:65], v[162:165], v[200:203], v[62:65]
	v_mfma_f32_16x16x32_bf16 v[58:61], v[192:195], v[200:203], v[58:61]
	v_mfma_f32_16x16x32_bf16 v[46:49], v[162:165], v[208:211], v[46:49]
	v_mfma_f32_16x16x32_bf16 v[42:45], v[192:195], v[208:211], v[42:45]
	v_mfma_f32_16x16x32_bf16 v[30:33], v[162:165], v[216:219], v[30:33]
	v_mfma_f32_16x16x32_bf16 v[26:29], v[192:195], v[216:219], v[26:29]
	v_mfma_f32_16x16x32_bf16 v[14:17], v[162:165], v[224:227], v[14:17]
	v_mfma_f32_16x16x32_bf16 v[10:13], v[192:195], v[224:227], v[10:13]
	s_setprio 0
	s_barrier
	s_add_u32 s42, s42, 0x80080
	s_addc_u32 s43, s43, 0
	s_add_i32 s44, s44, s28
	v_lshl_add_u64 v[158:159], s[42:43], 0, v[148:149]
	s_mov_b32 m0, s44
	s_nop 0
	global_load_lds_dwordx4 v[158:159], off
	v_lshl_add_u64 v[158:159], s[42:43], 0, v[150:151]
	s_add_i32 m0, s44, 0x2000
	s_nop 0
	global_load_lds_dwordx4 v[158:159], off
	s_waitcnt vmcnt(6)
	s_barrier
	s_setprio 1
	v_mfma_f32_16x16x32_bf16 v[54:57], v[228:231], v[196:199], v[54:57]
	v_mfma_f32_16x16x32_bf16 v[50:53], v[236:239], v[196:199], v[50:53]
	v_mfma_f32_16x16x32_bf16 v[38:41], v[228:231], v[204:207], v[38:41]
	v_mfma_f32_16x16x32_bf16 v[34:37], v[236:239], v[204:207], v[34:37]
	v_mfma_f32_16x16x32_bf16 v[22:25], v[228:231], v[212:215], v[22:25]
	v_mfma_f32_16x16x32_bf16 v[18:21], v[236:239], v[212:215], v[18:21]
	v_mfma_f32_16x16x32_bf16 v[6:9], v[228:231], v[220:223], v[6:9]
	v_mfma_f32_16x16x32_bf16 v[2:5], v[236:239], v[220:223], v[2:5]
	v_mfma_f32_16x16x32_bf16 v[54:57], v[232:235], v[200:203], v[54:57]
	v_mfma_f32_16x16x32_bf16 v[50:53], v[240:243], v[200:203], v[50:53]
	v_mfma_f32_16x16x32_bf16 v[38:41], v[232:235], v[208:211], v[38:41]
	v_mfma_f32_16x16x32_bf16 v[34:37], v[240:243], v[208:211], v[34:37]
	v_mfma_f32_16x16x32_bf16 v[22:25], v[232:235], v[216:219], v[22:25]
	v_mfma_f32_16x16x32_bf16 v[18:21], v[240:243], v[216:219], v[18:21]
	v_mfma_f32_16x16x32_bf16 v[6:9], v[232:235], v[224:227], v[6:9]
	v_mfma_f32_16x16x32_bf16 v[2:5], v[240:243], v[224:227], v[2:5]
	s_setprio 0
	s_add_i32 s49, s49, 2
	s_add_u32 s10, s10, 0x100
	s_addc_u32 s11, s11, 0
	s_add_u32 s47, s47, 0x100
	s_addc_u32 s48, s48, 0
	s_cmp_gt_u32 s49, 29
	s_barrier
	s_cbranch_scc0 .LBB0_294
	s_cmp_eq_u32 s6, 16
	s_cbranch_scc1 .Lbf_orig_r7in
;   __device__ __forceinline__ void operator()(const f32x4 (&acc)[2][2][4][2], const pg8::Unit& u, int wr, int wc, int fr, int fq) const {
; #pragma unroll
;     for (int ai = 0; ai < 2; ++ai)
; #pragma unroll
;       for (int m = 0; m < 4; ++m) { const int row = u.pm * 256 + ai * 128 + wr * 64 + m * 16 + fr;
; #pragma unroll
;         for (int bj = 0; bj < 2; ++bj)
; #pragma unroll
;           for (int n = 0; n < 2; ++n) f(row, u.pn * 256 + bj * 128 + wc * 32 + n * 16 + 4 * fq, acc[ai][bj][m][n]); }
;   }
	s_movk_i32 s7, 0x2000
	v_bfe_u32 v178, v168, 4, 1
	v_mul_u32_u24_e32 v178, 24, v178
	v_lshl_add_u32 v178, v152, 1, v178
	v_mad_u32_u24 v178, v147, s7, v178
	s_lshl_b32 s56, s62, 1
	v_add_u32_e32 v178, s56, v178
	s_lshl_b32 s10, s8, 21
	s_lshl_b32 s56, s6, 9
	s_add_i32 s10, s10, s56
	s_add_u32 s10, s38, s10
	s_addc_u32 s11, s39, 0
	v_cvt_pk_bf16_f32 v125, v124, v125
	v_cvt_pk_bf16_f32 v124, v122, v123
	v_cvt_pk_bf16_f32 v122, v126, v127
	v_cvt_pk_bf16_f32 v123, v128, v129
	v_cvt_pk_bf16_f32 v117, v116, v117
	v_cvt_pk_bf16_f32 v116, v114, v115
	v_cvt_pk_bf16_f32 v114, v118, v119
	v_cvt_pk_bf16_f32 v115, v120, v121
	v_permlane16_swap_b32_e32 v122, v124
	v_permlane16_swap_b32_e32 v123, v125
	v_permlane16_swap_b32_e32 v114, v116
	v_permlane16_swap_b32_e32 v115, v117
	global_store_dwordx4 v178, v[122:125], s[10:11]
	global_store_dwordx4 v178, v[114:117], s[10:11] offset:256
	s_add_u32 s10, s10, 0x20000
	s_addc_u32 s11, s11, 0
	v_cvt_pk_bf16_f32 v109, v108, v109
	v_cvt_pk_bf16_f32 v108, v106, v107
	v_cvt_pk_bf16_f32 v106, v110, v111
	v_cvt_pk_bf16_f32 v107, v112, v113
	v_cvt_pk_bf16_f32 v101, v100, v101
	v_cvt_pk_bf16_f32 v100, v98, v99
	v_cvt_pk_bf16_f32 v98, v102, v103
	v_cvt_pk_bf16_f32 v99, v104, v105
	v_permlane16_swap_b32_e32 v106, v108
	v_permlane16_swap_b32_e32 v107, v109
	v_permlane16_swap_b32_e32 v98, v100
	v_permlane16_swap_b32_e32 v99, v101
	global_store_dwordx4 v178, v[106:109], s[10:11]
	global_store_dwordx4 v178, v[98:101], s[10:11] offset:256
	s_add_u32 s10, s10, 0x20000
	s_addc_u32 s11, s11, 0
	v_cvt_pk_bf16_f32 v93, v92, v93
	v_cvt_pk_bf16_f32 v92, v90, v91
	v_cvt_pk_bf16_f32 v90, v94, v95
	v_cvt_pk_bf16_f32 v91, v96, v97
	v_cvt_pk_bf16_f32 v85, v84, v85
	v_cvt_pk_bf16_f32 v84, v82, v83
	v_cvt_pk_bf16_f32 v82, v86, v87
	v_cvt_pk_bf16_f32 v83, v88, v89
	v_permlane16_swap_b32_e32 v90, v92
	v_permlane16_swap_b32_e32 v91, v93
	v_permlane16_swap_b32_e32 v82, v84
	v_permlane16_swap_b32_e32 v83, v85
	global_store_dwordx4 v178, v[90:93], s[10:11]
	global_store_dwordx4 v178, v[82:85], s[10:11] offset:256
	s_add_u32 s10, s10, 0x20000
	s_addc_u32 s11, s11, 0
	v_cvt_pk_bf16_f32 v77, v76, v77
	v_cvt_pk_bf16_f32 v76, v74, v75
	v_cvt_pk_bf16_f32 v74, v78, v79
	v_cvt_pk_bf16_f32 v75, v80, v81
	v_cvt_pk_bf16_f32 v69, v68, v69
	v_cvt_pk_bf16_f32 v68, v66, v67
	v_cvt_pk_bf16_f32 v66, v70, v71
	v_cvt_pk_bf16_f32 v67, v72, v73
	v_permlane16_swap_b32_e32 v74, v76
	v_permlane16_swap_b32_e32 v75, v77
	v_permlane16_swap_b32_e32 v66, v68
	v_permlane16_swap_b32_e32 v67, v69
	global_store_dwordx4 v178, v[74:77], s[10:11]
	global_store_dwordx4 v178, v[66:69], s[10:11] offset:256
	s_add_u32 s10, s10, 0xa0000
	s_addc_u32 s11, s11, 0
	v_cvt_pk_bf16_f32 v61, v60, v61
	v_cvt_pk_bf16_f32 v60, v58, v59
	v_cvt_pk_bf16_f32 v58, v62, v63
	v_cvt_pk_bf16_f32 v59, v64, v65
	v_cvt_pk_bf16_f32 v53, v52, v53
	v_cvt_pk_bf16_f32 v52, v50, v51
	v_cvt_pk_bf16_f32 v50, v54, v55
	v_cvt_pk_bf16_f32 v51, v56, v57
	v_permlane16_swap_b32_e32 v58, v60
	v_permlane16_swap_b32_e32 v59, v61
	v_permlane16_swap_b32_e32 v50, v52
	v_permlane16_swap_b32_e32 v51, v53
	global_store_dwordx4 v178, v[58:61], s[10:11]
	global_store_dwordx4 v178, v[50:53], s[10:11] offset:256
	s_add_u32 s10, s10, 0x20000
	s_addc_u32 s11, s11, 0
	v_cvt_pk_bf16_f32 v45, v44, v45
	v_cvt_pk_bf16_f32 v44, v42, v43
	v_cvt_pk_bf16_f32 v42, v46, v47
	v_cvt_pk_bf16_f32 v43, v48, v49
	v_cvt_pk_bf16_f32 v37, v36, v37
	v_cvt_pk_bf16_f32 v36, v34, v35
	v_cvt_pk_bf16_f32 v34, v38, v39
	v_cvt_pk_bf16_f32 v35, v40, v41
	v_permlane16_swap_b32_e32 v42, v44
	v_permlane16_swap_b32_e32 v43, v45
	v_permlane16_swap_b32_e32 v34, v36
	v_permlane16_swap_b32_e32 v35, v37
	global_store_dwordx4 v178, v[42:45], s[10:11]
	global_store_dwordx4 v178, v[34:37], s[10:11] offset:256
	s_add_u32 s10, s10, 0x20000
	s_addc_u32 s11, s11, 0
	v_cvt_pk_bf16_f32 v29, v28, v29
	v_cvt_pk_bf16_f32 v28, v26, v27
	v_cvt_pk_bf16_f32 v26, v30, v31
	v_cvt_pk_bf16_f32 v27, v32, v33
	v_cvt_pk_bf16_f32 v21, v20, v21
	v_cvt_pk_bf16_f32 v20, v18, v19
	v_cvt_pk_bf16_f32 v18, v22, v23
	v_cvt_pk_bf16_f32 v19, v24, v25
	v_permlane16_swap_b32_e32 v26, v28
	v_permlane16_swap_b32_e32 v27, v29
	v_permlane16_swap_b32_e32 v18, v20
	v_permlane16_swap_b32_e32 v19, v21
	global_store_dwordx4 v178, v[26:29], s[10:11]
	global_store_dwordx4 v178, v[18:21], s[10:11] offset:256
	s_add_u32 s10, s10, 0x20000
	s_addc_u32 s11, s11, 0
	v_cvt_pk_bf16_f32 v13, v12, v13
	v_cvt_pk_bf16_f32 v12, v10, v11
	v_cvt_pk_bf16_f32 v10, v14, v15
	v_cvt_pk_bf16_f32 v11, v16, v17
	v_cvt_pk_bf16_f32 v5, v4, v5
	v_cvt_pk_bf16_f32 v4, v2, v3
	v_cvt_pk_bf16_f32 v2, v6, v7
	v_cvt_pk_bf16_f32 v3, v8, v9
	v_permlane16_swap_b32_e32 v10, v12
	v_permlane16_swap_b32_e32 v11, v13
	v_permlane16_swap_b32_e32 v2, v4
	v_permlane16_swap_b32_e32 v3, v5
	global_store_dwordx4 v178, v[10:13], s[10:11]
	global_store_dwordx4 v178, v[2:5], s[10:11] offset:256
	s_branch .LBB0_286
.Lbf_orig_r7in:
	s_lshl_b32 s10, s6, 8
	v_lshl_add_u32 v160, s8, 8, v147
	s_or_b32 s56, s10, s62
	v_ashrrev_i32_e32 v161, 31, v160
	v_or_b32_e32 v0, s56, v152
	s_movk_i32 s6, 0xfff
	v_lshlrev_b64 v[162:163], 8, v[160:161]
	v_cmp_lt_i32_e64 s[42:43], s6, v0
	s_and_saveexec_b64 s[6:7], s[42:43]
	s_xor_b64 s[6:7], exec, s[6:7]
	s_cbranch_execz .LBB0_316
	s_cmpk_gt_u32 s10, 0x107f
	s_mov_b64 s[8:9], -1
	s_cbranch_scc0 .LBB0_298
	v_lshl_add_u64 v[158:159], s[26:27], 0, v[162:163]
	v_lshl_add_u64 v[158:159], v[0:1], 1, v[158:159]
	v_add_co_u32_e32 v158, vcc, 0x14d1d000, v158
	v_cvt_pk_bf16_f32 v164, v126, v127
	v_cvt_pk_bf16_f32 v165, v128, v129
	v_addc_co_u32_e32 v159, vcc, 0, v159, vcc
	global_store_dwordx2 v[158:159], v[164:165], off offset:3840
	s_mov_b64 s[8:9], 0

; #define PG8_STAGE(bufoff, gbase, voff) do { _Pragma("unroll") for (int _i = 0; _i < 2; ++_i) \
;     __builtin_amdgcn_global_load_lds((const unsigned*)((const char*)(gbase) + (voff)[_i]), (PG8_LAS unsigned*)(lds + (bufoff) + ldsw + _i * 8192), 16, 0, 0); } while (0)
; #define PG8_LDA(dst, b, h) do { _Pragma("unroll") for (int m = 0; m < 4; ++m) _Pragma("unroll") for (int k = 0; k < 2; ++k) dst[m][k] = *(const PG8_LAS bf16x8*)(lds + PG8_SA(b, h) + aoff + m * 2048 + k * 1024); } while (0)
; #define PG8_LDB(dst, b, h) do { _Pragma("unroll") for (int n = 0; n < 2; ++n) _Pragma("unroll") for (int k = 0; k < 2; ++k) dst[n][k] = *(const PG8_LAS bf16x8*)(lds + PG8_SB(b, h) + boff + n * 2048 + k * 1024); } while (0)
; #define PG8_BAR __builtin_amdgcn_s_barrier()
; template <class Epi>
; __device__ __forceinline__ void gemm_phase(PG8_LAS unsigned char* lds, const Gemm g, const StaticOrder& S, const Epi& E) {
;     ...
;     for (int t = 0; t < nt; t += 2) {
;       const bool last = (t == nt - 2);
;       const char* a1 = cA + (size_t)(t + 1) * kstep;
;       const char* a2 = last ? nA : cA + (size_t)(t + 2) * kstep; const char* b2 = last ? nB : cB + (size_t)(t + 2) * kstep;
;       const char* a3 = a2 + kstep; const char* b3 = b2 + kstep;
;       PG8_LDB(B0, 0, 0); PG8_SCHED; PG8_LDA(At, 0, 0); PG8_STAGE(PG8_SA(1, 1), a1 + hstep, voffA);
;       PG8_WAIT_L(8); PG8_BAR; PG8_WAIT_L(0); PG8_MMA(0, 0, At, B0); PG8_BAR; PG8_SCHED;
;       PG8_LDB(B1, 0, 1); PG8_STAGE(PG8_SB(0, 0), b2, voffB);
;       PG8_BAR; PG8_WAIT_L(0); PG8_MMA(0, 1, At, B1); PG8_BAR;
;       PG8_LDA(At, 0, 1); PG8_STAGE(PG8_SA(0, 0), a2, voffA);
;       PG8_BAR; PG8_WAIT_L(0); PG8_MMA(1, 0, At, B0); PG8_BAR; PG8_SCHED;
;       PG8_STAGE(PG8_SB(0, 1), b2 + hstep, voffB);
;       PG8_WAIT_V(6); PG8_BAR; PG8_MMA(1, 1, At, B1); PG8_BAR;
;       PG8_LDB(B0, 1, 0); PG8_SCHED; PG8_LDA(At, 1, 0); PG8_STAGE(PG8_SA(0, 1), a2 + hstep, voffA);
;       PG8_WAIT_L(8); PG8_BAR; PG8_WAIT_L(0); PG8_MMA(0, 0, At, B0); PG8_BAR; PG8_SCHED;
;       PG8_LDB(B1, 1, 1); PG8_STAGE(PG8_SB(1, 0), b3, voffB);
;       PG8_BAR; PG8_WAIT_L(0); PG8_MMA(0, 1, At, B1); PG8_BAR;
;       PG8_LDA(At, 1, 1); PG8_STAGE(PG8_SA(1, 0), a3, voffA);
;       PG8_BAR; PG8_WAIT_L(0); PG8_MMA(1, 0, At, B0); PG8_BAR; PG8_SCHED;
;       PG8_STAGE(PG8_SB(1, 1), b3 + hstep, voffB);
;       PG8_WAIT_V(6); PG8_BAR; PG8_MMA(1, 1, At, B1); PG8_BAR;
;     }
.LBB0_1230:
	s_add_u32 s48, s46, 0xfffc0080
	s_addc_u32 s49, s47, -1
	s_add_i32 s63, 0, 0x10000
	v_add_u32_e32 v0, s63, v166
	ds_read_b128 v[158:161], v0
	ds_read_b128 v[162:165], v0 offset:1024
	ds_read_b128 v[188:191], v0 offset:2048
	ds_read_b128 v[192:195], v0 offset:3072
	s_cmp_eq_u32 s62, 12
	s_cselect_b32 s51, s9, s49
	s_cselect_b32 s50, s43, s48
	s_cselect_b32 s49, s7, s53
	s_cselect_b32 s48, s45, s52
	v_lshl_add_u64 v[178:179], s[46:47], 0, v[154:155]
	s_add_i32 m0, s54, 0xc000
	ds_read_b128 v[196:199], v167
	ds_read_b128 v[200:203], v167 offset:1024
	ds_read_b128 v[204:207], v167 offset:2048
	ds_read_b128 v[208:211], v167 offset:3072
	ds_read_b128 v[212:215], v167 offset:4096
	ds_read_b128 v[216:219], v167 offset:5120
	ds_read_b128 v[220:223], v167 offset:6144
	ds_read_b128 v[224:227], v167 offset:7168
	global_load_lds_dwordx4 v[178:179], off
	v_lshl_add_u64 v[178:179], s[46:47], 0, v[156:157]
	s_add_i32 m0, s54, 0xe000
	s_nop 0
	global_load_lds_dwordx4 v[178:179], off
	s_waitcnt lgkmcnt(8)
	s_barrier
	s_waitcnt lgkmcnt(0)
	s_setprio 1
	s_waitcnt lgkmcnt(0)
	v_mfma_f32_16x16x32_bf16 v[126:129], v[158:161], v[196:199], v[126:129]
	v_mfma_f32_16x16x32_bf16 v[122:125], v[188:191], v[196:199], v[122:125]
	v_mfma_f32_16x16x32_bf16 v[110:113], v[158:161], v[204:207], v[110:113]
	v_mfma_f32_16x16x32_bf16 v[106:109], v[188:191], v[204:207], v[106:109]
	v_mfma_f32_16x16x32_bf16 v[94:97], v[158:161], v[212:215], v[94:97]
	v_mfma_f32_16x16x32_bf16 v[90:93], v[188:191], v[212:215], v[90:93]
	v_mfma_f32_16x16x32_bf16 v[78:81], v[158:161], v[220:223], v[78:81]
	v_mfma_f32_16x16x32_bf16 v[74:77], v[188:191], v[220:223], v[74:77]
	v_mfma_f32_16x16x32_bf16 v[126:129], v[162:165], v[200:203], v[126:129]
	v_mfma_f32_16x16x32_bf16 v[122:125], v[192:195], v[200:203], v[122:125]
	v_mfma_f32_16x16x32_bf16 v[110:113], v[162:165], v[208:211], v[110:113]
	v_mfma_f32_16x16x32_bf16 v[106:109], v[192:195], v[208:211], v[106:109]
	v_mfma_f32_16x16x32_bf16 v[94:97], v[162:165], v[216:219], v[94:97]
	v_mfma_f32_16x16x32_bf16 v[90:93], v[192:195], v[216:219], v[90:93]
	v_mfma_f32_16x16x32_bf16 v[78:81], v[162:165], v[224:227], v[78:81]
	v_mfma_f32_16x16x32_bf16 v[74:77], v[192:195], v[224:227], v[74:77]
	s_setprio 0
	s_barrier
	s_add_i32 s66, 0, 0x14000
	s_add_i32 s63, s63, s28
	v_add_u32_e32 v0, s66, v166
	v_lshl_add_u64 v[178:179], s[48:49], 0, v[148:149]
	s_mov_b32 m0, s63
	ds_read_b128 v[228:231], v0
	ds_read_b128 v[232:235], v0 offset:1024
	ds_read_b128 v[236:239], v0 offset:2048
	ds_read_b128 v[240:243], v0 offset:3072
	global_load_lds_dwordx4 v[178:179], off
	v_lshl_add_u64 v[244:245], s[48:49], 0, v[150:151]
	s_add_i32 m0, s63, 0x2000
	s_nop 0
	global_load_lds_dwordx4 v[244:245], off
	s_barrier
	s_waitcnt lgkmcnt(0)
	s_setprio 1
	s_waitcnt lgkmcnt(0)
	v_mfma_f32_16x16x32_bf16 v[118:121], v[228:231], v[196:199], v[118:121]
	v_mfma_f32_16x16x32_bf16 v[114:117], v[236:239], v[196:199], v[114:117]
	v_mfma_f32_16x16x32_bf16 v[102:105], v[228:231], v[204:207], v[102:105]
	v_mfma_f32_16x16x32_bf16 v[98:101], v[236:239], v[204:207], v[98:101]
	v_mfma_f32_16x16x32_bf16 v[86:89], v[228:231], v[212:215], v[86:89]
	v_mfma_f32_16x16x32_bf16 v[82:85], v[236:239], v[212:215], v[82:85]
	v_mfma_f32_16x16x32_bf16 v[70:73], v[228:231], v[220:223], v[70:73]
	v_mfma_f32_16x16x32_bf16 v[66:69], v[236:239], v[220:223], v[66:69]
	v_mfma_f32_16x16x32_bf16 v[118:121], v[232:235], v[200:203], v[118:121]
	v_mfma_f32_16x16x32_bf16 v[114:117], v[240:243], v[200:203], v[114:117]
	v_mfma_f32_16x16x32_bf16 v[102:105], v[232:235], v[208:211], v[102:105]
	v_mfma_f32_16x16x32_bf16 v[98:101], v[240:243], v[208:211], v[98:101]
	v_mfma_f32_16x16x32_bf16 v[86:89], v[232:235], v[216:219], v[86:89]
	v_mfma_f32_16x16x32_bf16 v[82:85], v[240:243], v[216:219], v[82:85]
	v_mfma_f32_16x16x32_bf16 v[70:73], v[232:235], v[224:227], v[70:73]
	v_mfma_f32_16x16x32_bf16 v[66:69], v[240:243], v[224:227], v[66:69]
	s_setprio 0
	s_mov_b32 m0, s54
	v_lshl_add_u64 v[246:247], s[50:51], 0, v[148:149]
	s_barrier
	ds_read_b128 v[196:199], v167 offset:16384
	ds_read_b128 v[200:203], v167 offset:17408
	ds_read_b128 v[204:207], v167 offset:18432
	ds_read_b128 v[208:211], v167 offset:19456
	ds_read_b128 v[212:215], v167 offset:20480
	ds_read_b128 v[216:219], v167 offset:21504
	ds_read_b128 v[220:223], v167 offset:22528
	ds_read_b128 v[224:227], v167 offset:23552
	global_load_lds_dwordx4 v[246:247], off
	v_lshl_add_u64 v[248:249], s[50:51], 0, v[150:151]
	s_mov_b32 m0, s55
	s_nop 0
	global_load_lds_dwordx4 v[248:249], off
	s_barrier
	s_waitcnt lgkmcnt(0)
	s_setprio 1
	s_waitcnt lgkmcnt(0)
	v_mfma_f32_16x16x32_bf16 v[62:65], v[158:161], v[196:199], v[62:65]
	v_mfma_f32_16x16x32_bf16 v[58:61], v[188:191], v[196:199], v[58:61]
	v_mfma_f32_16x16x32_bf16 v[46:49], v[158:161], v[204:207], v[46:49]
	v_mfma_f32_16x16x32_bf16 v[42:45], v[188:191], v[204:207], v[42:45]
	v_mfma_f32_16x16x32_bf16 v[30:33], v[158:161], v[212:215], v[30:33]
	v_mfma_f32_16x16x32_bf16 v[26:29], v[188:191], v[212:215], v[26:29]
	v_mfma_f32_16x16x32_bf16 v[14:17], v[158:161], v[220:223], v[14:17]
	v_mfma_f32_16x16x32_bf16 v[10:13], v[188:191], v[220:223], v[10:13]
	v_mfma_f32_16x16x32_bf16 v[62:65], v[162:165], v[200:203], v[62:65]
	v_mfma_f32_16x16x32_bf16 v[58:61], v[192:195], v[200:203], v[58:61]
	v_mfma_f32_16x16x32_bf16 v[46:49], v[162:165], v[208:211], v[46:49]
	v_mfma_f32_16x16x32_bf16 v[42:45], v[192:195], v[208:211], v[42:45]
	v_mfma_f32_16x16x32_bf16 v[30:33], v[162:165], v[216:219], v[30:33]
	v_mfma_f32_16x16x32_bf16 v[26:29], v[192:195], v[216:219], v[26:29]
	v_mfma_f32_16x16x32_bf16 v[14:17], v[162:165], v[224:227], v[14:17]
	v_mfma_f32_16x16x32_bf16 v[10:13], v[192:195], v[224:227], v[10:13]
	s_setprio 0
	s_barrier
; #define PG8_STAGE(bufoff, gbase, voff) do { _Pragma("unroll") for (int _i = 0; _i < 2; ++_i) \
;     __builtin_amdgcn_global_load_lds((const unsigned*)((const char*)(gbase) + (voff)[_i]), (PG8_LAS unsigned*)(lds + (bufoff) + ldsw + _i * 8192), 16, 0, 0); } while (0)
; #define PG8_LDA(dst, b, h) do { _Pragma("unroll") for (int m = 0; m < 4; ++m) _Pragma("unroll") for (int k = 0; k < 2; ++k) dst[m][k] = *(const PG8_LAS bf16x8*)(lds + PG8_SA(b, h) + aoff + m * 2048 + k * 1024); } while (0)
; #define PG8_LDB(dst, b, h) do { _Pragma("unroll") for (int n = 0; n < 2; ++n) _Pragma("unroll") for (int k = 0; k < 2; ++k) dst[n][k] = *(const PG8_LAS bf16x8*)(lds + PG8_SB(b, h) + boff + n * 2048 + k * 1024); } while (0)
; #define PG8_BAR __builtin_amdgcn_s_barrier()
; template <class Epi>
; __device__ __forceinline__ void gemm_phase(PG8_LAS unsigned char* lds, const Gemm g, const StaticOrder& S, const Epi& E) {
;     ...
;     for (int t = 0; t < nt; t += 2) {
;       const bool last = (t == nt - 2);
;       const char* a1 = cA + (size_t)(t + 1) * kstep;
;       const char* a2 = last ? nA : cA + (size_t)(t + 2) * kstep; const char* b2 = last ? nB : cB + (size_t)(t + 2) * kstep;
;       const char* a3 = a2 + kstep; const char* b3 = b2 + kstep;
;       PG8_LDB(B0, 0, 0); PG8_SCHED; PG8_LDA(At, 0, 0); PG8_STAGE(PG8_SA(1, 1), a1 + hstep, voffA);
;       PG8_WAIT_L(8); PG8_BAR; PG8_WAIT_L(0); PG8_MMA(0, 0, At, B0); PG8_BAR; PG8_SCHED;
;       PG8_LDB(B1, 0, 1); PG8_STAGE(PG8_SB(0, 0), b2, voffB);
;       PG8_BAR; PG8_WAIT_L(0); PG8_MMA(0, 1, At, B1); PG8_BAR;
;       PG8_LDA(At, 0, 1); PG8_STAGE(PG8_SA(0, 0), a2, voffA);
;       PG8_BAR; PG8_WAIT_L(0); PG8_MMA(1, 0, At, B0); PG8_BAR; PG8_SCHED;
;       PG8_STAGE(PG8_SB(0, 1), b2 + hstep, voffB);
;       PG8_WAIT_V(6); PG8_BAR; PG8_MMA(1, 1, At, B1); PG8_BAR;
;       PG8_LDB(B0, 1, 0); PG8_SCHED; PG8_LDA(At, 1, 0); PG8_STAGE(PG8_SA(0, 1), a2 + hstep, voffA);
;       PG8_WAIT_L(8); PG8_BAR; PG8_WAIT_L(0); PG8_MMA(0, 0, At, B0); PG8_BAR; PG8_SCHED;
;       PG8_LDB(B1, 1, 1); PG8_STAGE(PG8_SB(1, 0), b3, voffB);
;       PG8_BAR; PG8_WAIT_L(0); PG8_MMA(0, 1, At, B1); PG8_BAR;
;       PG8_LDA(At, 1, 1); PG8_STAGE(PG8_SA(1, 0), a3, voffA);
;       PG8_BAR; PG8_WAIT_L(0); PG8_MMA(1, 0, At, B0); PG8_BAR; PG8_SCHED;
;       PG8_STAGE(PG8_SB(1, 1), b3 + hstep, voffB);
;       PG8_WAIT_V(6); PG8_BAR; PG8_MMA(1, 1, At, B1); PG8_BAR;
;     }
	s_add_u32 s64, s48, 0x40000
	s_addc_u32 s65, s49, 0
	s_add_i32 s63, s66, s28
	v_lshl_add_u64 v[158:159], s[64:65], 0, v[148:149]
	s_mov_b32 m0, s63
	s_nop 0
	global_load_lds_dwordx4 v[158:159], off
	v_lshl_add_u64 v[158:159], s[64:65], 0, v[150:151]
	s_add_i32 m0, s63, 0x2000
	s_nop 0
	global_load_lds_dwordx4 v[158:159], off
	s_waitcnt vmcnt(6)
	s_barrier
	s_setprio 1
	v_mfma_f32_16x16x32_bf16 v[54:57], v[228:231], v[196:199], v[54:57]
	v_mfma_f32_16x16x32_bf16 v[50:53], v[236:239], v[196:199], v[50:53]
	v_mfma_f32_16x16x32_bf16 v[38:41], v[228:231], v[204:207], v[38:41]
	v_mfma_f32_16x16x32_bf16 v[34:37], v[236:239], v[204:207], v[34:37]
	v_mfma_f32_16x16x32_bf16 v[22:25], v[228:231], v[212:215], v[22:25]
	v_mfma_f32_16x16x32_bf16 v[18:21], v[236:239], v[212:215], v[18:21]
	v_mfma_f32_16x16x32_bf16 v[6:9], v[228:231], v[220:223], v[6:9]
	v_mfma_f32_16x16x32_bf16 v[2:5], v[236:239], v[220:223], v[2:5]
	v_mfma_f32_16x16x32_bf16 v[54:57], v[232:235], v[200:203], v[54:57]
	v_mfma_f32_16x16x32_bf16 v[50:53], v[240:243], v[200:203], v[50:53]
	v_mfma_f32_16x16x32_bf16 v[38:41], v[232:235], v[208:211], v[38:41]
	v_mfma_f32_16x16x32_bf16 v[34:37], v[240:243], v[208:211], v[34:37]
	v_mfma_f32_16x16x32_bf16 v[22:25], v[232:235], v[216:219], v[22:25]
	v_mfma_f32_16x16x32_bf16 v[18:21], v[240:243], v[216:219], v[18:21]
	v_mfma_f32_16x16x32_bf16 v[6:9], v[232:235], v[224:227], v[6:9]
	v_mfma_f32_16x16x32_bf16 v[2:5], v[240:243], v[224:227], v[2:5]
	s_setprio 0
	s_add_i32 s63, 0, 0x18000
	v_add_u32_e32 v0, s63, v166
	s_barrier
	ds_read_b128 v[158:161], v0
	ds_read_b128 v[162:165], v0 offset:1024
	ds_read_b128 v[188:191], v0 offset:2048
	ds_read_b128 v[192:195], v0 offset:3072
	s_add_u32 s50, s50, 0x40000
	s_addc_u32 s51, s51, 0
	s_mov_b32 m0, s56
	v_lshl_add_u64 v[228:229], s[50:51], 0, v[148:149]
	ds_read_b128 v[196:199], v167 offset:32768
	ds_read_b128 v[200:203], v167 offset:33792
	ds_read_b128 v[204:207], v167 offset:34816
	ds_read_b128 v[208:211], v167 offset:35840
	ds_read_b128 v[212:215], v167 offset:36864
	ds_read_b128 v[216:219], v167 offset:37888
	ds_read_b128 v[220:223], v167 offset:38912
	ds_read_b128 v[224:227], v167 offset:39936
	global_load_lds_dwordx4 v[228:229], off
	v_lshl_add_u64 v[228:229], s[50:51], 0, v[150:151]
	s_mov_b32 m0, s57
	s_nop 0
	global_load_lds_dwordx4 v[228:229], off
	s_waitcnt lgkmcnt(8)
	s_barrier
	s_waitcnt lgkmcnt(0)
	s_setprio 1
	s_waitcnt lgkmcnt(0)
	v_mfma_f32_16x16x32_bf16 v[126:129], v[158:161], v[196:199], v[126:129]
	v_mfma_f32_16x16x32_bf16 v[122:125], v[188:191], v[196:199], v[122:125]
	v_mfma_f32_16x16x32_bf16 v[110:113], v[158:161], v[204:207], v[110:113]
	v_mfma_f32_16x16x32_bf16 v[106:109], v[188:191], v[204:207], v[106:109]
	v_mfma_f32_16x16x32_bf16 v[94:97], v[158:161], v[212:215], v[94:97]
	v_mfma_f32_16x16x32_bf16 v[90:93], v[188:191], v[212:215], v[90:93]
	v_mfma_f32_16x16x32_bf16 v[78:81], v[158:161], v[220:223], v[78:81]
	v_mfma_f32_16x16x32_bf16 v[74:77], v[188:191], v[220:223], v[74:77]
	v_mfma_f32_16x16x32_bf16 v[126:129], v[162:165], v[200:203], v[126:129]
	v_mfma_f32_16x16x32_bf16 v[122:125], v[192:195], v[200:203], v[122:125]
	v_mfma_f32_16x16x32_bf16 v[110:113], v[162:165], v[208:211], v[110:113]
	v_mfma_f32_16x16x32_bf16 v[106:109], v[192:195], v[208:211], v[106:109]
	v_mfma_f32_16x16x32_bf16 v[94:97], v[162:165], v[216:219], v[94:97]
	v_mfma_f32_16x16x32_bf16 v[90:93], v[192:195], v[216:219], v[90:93]
	v_mfma_f32_16x16x32_bf16 v[78:81], v[162:165], v[224:227], v[78:81]
	v_mfma_f32_16x16x32_bf16 v[74:77], v[192:195], v[224:227], v[74:77]
	s_setprio 0
	s_barrier
	s_add_i32 s50, 0, 0x1c000
	s_add_i32 s51, s63, s28
	v_add_u32_e32 v0, s50, v166
	v_lshl_add_u64 v[178:179], v[178:179], 0, s[4:5]
	s_mov_b32 m0, s51
	ds_read_b128 v[228:231], v0
	ds_read_b128 v[232:235], v0 offset:1024
	ds_read_b128 v[236:239], v0 offset:2048
	ds_read_b128 v[240:243], v0 offset:3072
	global_load_lds_dwordx4 v[178:179], off
	v_lshl_add_u64 v[178:179], v[244:245], 0, s[4:5]
	s_add_i32 m0, s51, 0x2000
	s_nop 0
	global_load_lds_dwordx4 v[178:179], off
	s_barrier
	s_waitcnt lgkmcnt(0)
	s_setprio 1
	s_waitcnt lgkmcnt(0)
	v_mfma_f32_16x16x32_bf16 v[118:121], v[228:231], v[196:199], v[118:121]
	v_mfma_f32_16x16x32_bf16 v[114:117], v[236:239], v[196:199], v[114:117]
	v_mfma_f32_16x16x32_bf16 v[102:105], v[228:231], v[204:207], v[102:105]
	v_mfma_f32_16x16x32_bf16 v[98:101], v[236:239], v[204:207], v[98:101]
	v_mfma_f32_16x16x32_bf16 v[86:89], v[228:231], v[212:215], v[86:89]
	v_mfma_f32_16x16x32_bf16 v[82:85], v[236:239], v[212:215], v[82:85]
	v_mfma_f32_16x16x32_bf16 v[70:73], v[228:231], v[220:223], v[70:73]
	v_mfma_f32_16x16x32_bf16 v[66:69], v[236:239], v[220:223], v[66:69]
	v_mfma_f32_16x16x32_bf16 v[118:121], v[232:235], v[200:203], v[118:121]
	v_mfma_f32_16x16x32_bf16 v[114:117], v[240:243], v[200:203], v[114:117]
	v_mfma_f32_16x16x32_bf16 v[102:105], v[232:235], v[208:211], v[102:105]
	v_mfma_f32_16x16x32_bf16 v[98:101], v[240:243], v[208:211], v[98:101]
	v_mfma_f32_16x16x32_bf16 v[86:89], v[232:235], v[216:219], v[86:89]
	v_mfma_f32_16x16x32_bf16 v[82:85], v[240:243], v[216:219], v[82:85]
	v_mfma_f32_16x16x32_bf16 v[70:73], v[232:235], v[224:227], v[70:73]
	v_mfma_f32_16x16x32_bf16 v[66:69], v[240:243], v[224:227], v[66:69]
	s_setprio 0
	s_mov_b32 m0, s59
	v_lshl_add_u64 v[178:179], v[246:247], 0, s[4:5]
	s_barrier
	ds_read_b128 v[196:199], v167 offset:49152
	ds_read_b128 v[200:203], v167 offset:50176
	ds_read_b128 v[204:207], v167 offset:51200
	ds_read_b128 v[208:211], v167 offset:52224
	ds_read_b128 v[212:215], v167 offset:53248
	ds_read_b128 v[216:219], v167 offset:54272
	ds_read_b128 v[220:223], v167 offset:55296
	ds_read_b128 v[224:227], v167 offset:56320
	global_load_lds_dwordx4 v[178:179], off
	v_lshl_add_u64 v[178:179], v[248:249], 0, s[4:5]
	s_mov_b32 m0, s60
	s_nop 0
	global_load_lds_dwordx4 v[178:179], off
	s_barrier
; #define PG8_STAGE(bufoff, gbase, voff) do { _Pragma("unroll") for (int _i = 0; _i < 2; ++_i) \
;     __builtin_amdgcn_global_load_lds((const unsigned*)((const char*)(gbase) + (voff)[_i]), (PG8_LAS unsigned*)(lds + (bufoff) + ldsw + _i * 8192), 16, 0, 0); } while (0)
; #define PG8_LDA(dst, b, h) do { _Pragma("unroll") for (int m = 0; m < 4; ++m) _Pragma("unroll") for (int k = 0; k < 2; ++k) dst[m][k] = *(const PG8_LAS bf16x8*)(lds + PG8_SA(b, h) + aoff + m * 2048 + k * 1024); } while (0)
; #define PG8_LDB(dst, b, h) do { _Pragma("unroll") for (int n = 0; n < 2; ++n) _Pragma("unroll") for (int k = 0; k < 2; ++k) dst[n][k] = *(const PG8_LAS bf16x8*)(lds + PG8_SB(b, h) + boff + n * 2048 + k * 1024); } while (0)
; #define PG8_MMA(ai, bj, At, Bt) do { __builtin_amdgcn_s_setprio(1); _Pragma("unroll") for (int m = 0; m < 4; ++m) _Pragma("unroll") for (int n = 0; n < 2; ++n) _Pragma("unroll") for (int k = 0; k < 2; ++k) \
;     acc[ai][bj][m][n] = __builtin_amdgcn_mfma_f32_16x16x32_bf16(Bt[n][k], At[m][k], acc[ai][bj][m][n], 0, 0, 0); __builtin_amdgcn_s_setprio(0); } while (0)
; template <class Epi>
; __device__ __forceinline__ void gemm_phase(PG8_LAS unsigned char* lds, const Gemm g, const StaticOrder& S, const Epi& E) {
;     ...
;       PG8_LDB(B0, 0, 0); PG8_SCHED; PG8_LDA(At, 0, 0); PG8_STAGE(PG8_SA(1, 1), a1 + hstep, voffA);
;       PG8_WAIT_L(8); PG8_BAR; PG8_WAIT_L(0); PG8_MMA(0, 0, At, B0); PG8_BAR; PG8_SCHED;
;       PG8_LDB(B1, 0, 1); PG8_STAGE(PG8_SB(0, 0), b2, voffB);
;       PG8_BAR; PG8_WAIT_L(0); PG8_MMA(0, 1, At, B1); PG8_BAR;
;       PG8_LDA(At, 0, 1); PG8_STAGE(PG8_SA(0, 0), a2, voffA);
;       PG8_BAR; PG8_WAIT_L(0); PG8_MMA(1, 0, At, B0); PG8_BAR; PG8_SCHED;
;       PG8_STAGE(PG8_SB(0, 1), b2 + hstep, voffB);
;       PG8_WAIT_V(6); PG8_BAR; PG8_MMA(1, 1, At, B1); PG8_BAR;
;       PG8_LDB(B0, 1, 0); PG8_SCHED; PG8_LDA(At, 1, 0); PG8_STAGE(PG8_SA(0, 1), a2 + hstep, voffA);
;       PG8_WAIT_L(8); PG8_BAR; PG8_WAIT_L(0); PG8_MMA(0, 0, At, B0); PG8_BAR; PG8_SCHED;
;       PG8_LDB(B1, 1, 1); PG8_STAGE(PG8_SB(1, 0), b3, voffB);
;       PG8_BAR; PG8_WAIT_L(0); PG8_MMA(0, 1, At, B1); PG8_BAR;
;       PG8_LDA(At, 1, 1); PG8_STAGE(PG8_SA(1, 0), a3, voffA);
;       PG8_BAR; PG8_WAIT_L(0); PG8_MMA(1, 0, At, B0); PG8_BAR; PG8_SCHED;
;       PG8_STAGE(PG8_SB(1, 1), b3 + hstep, voffB);
;       PG8_WAIT_V(6); PG8_BAR; PG8_MMA(1, 1, At, B1); PG8_BAR;
;     }
	s_waitcnt lgkmcnt(0)
	s_setprio 1
	s_waitcnt lgkmcnt(0)
	v_mfma_f32_16x16x32_bf16 v[62:65], v[158:161], v[196:199], v[62:65]
	v_mfma_f32_16x16x32_bf16 v[58:61], v[188:191], v[196:199], v[58:61]
	v_mfma_f32_16x16x32_bf16 v[46:49], v[158:161], v[204:207], v[46:49]
	v_mfma_f32_16x16x32_bf16 v[42:45], v[188:191], v[204:207], v[42:45]
	v_mfma_f32_16x16x32_bf16 v[30:33], v[158:161], v[212:215], v[30:33]
	v_mfma_f32_16x16x32_bf16 v[26:29], v[188:191], v[212:215], v[26:29]
	v_mfma_f32_16x16x32_bf16 v[14:17], v[158:161], v[220:223], v[14:17]
	v_mfma_f32_16x16x32_bf16 v[10:13], v[188:191], v[220:223], v[10:13]
	v_mfma_f32_16x16x32_bf16 v[62:65], v[162:165], v[200:203], v[62:65]
	v_mfma_f32_16x16x32_bf16 v[58:61], v[192:195], v[200:203], v[58:61]
	v_mfma_f32_16x16x32_bf16 v[46:49], v[162:165], v[208:211], v[46:49]
	v_mfma_f32_16x16x32_bf16 v[42:45], v[192:195], v[208:211], v[42:45]
	v_mfma_f32_16x16x32_bf16 v[30:33], v[162:165], v[216:219], v[30:33]
	v_mfma_f32_16x16x32_bf16 v[26:29], v[192:195], v[216:219], v[26:29]
	v_mfma_f32_16x16x32_bf16 v[14:17], v[162:165], v[224:227], v[14:17]
	v_mfma_f32_16x16x32_bf16 v[10:13], v[192:195], v[224:227], v[10:13]
	s_setprio 0
	s_barrier
	s_add_u32 s48, s48, 0x40080
	s_addc_u32 s49, s49, 0
	s_add_i32 s50, s50, s28
	v_lshl_add_u64 v[158:159], s[48:49], 0, v[148:149]
	s_mov_b32 m0, s50
	s_nop 0
	global_load_lds_dwordx4 v[158:159], off
	v_lshl_add_u64 v[158:159], s[48:49], 0, v[150:151]
	s_add_i32 m0, s50, 0x2000
	s_nop 0
	global_load_lds_dwordx4 v[158:159], off
	s_waitcnt vmcnt(6)
	s_barrier
	s_setprio 1
	v_mfma_f32_16x16x32_bf16 v[54:57], v[228:231], v[196:199], v[54:57]
	v_mfma_f32_16x16x32_bf16 v[50:53], v[236:239], v[196:199], v[50:53]
	v_mfma_f32_16x16x32_bf16 v[38:41], v[228:231], v[204:207], v[38:41]
	v_mfma_f32_16x16x32_bf16 v[34:37], v[236:239], v[204:207], v[34:37]
	v_mfma_f32_16x16x32_bf16 v[22:25], v[228:231], v[212:215], v[22:25]
	v_mfma_f32_16x16x32_bf16 v[18:21], v[236:239], v[212:215], v[18:21]
	v_mfma_f32_16x16x32_bf16 v[6:9], v[228:231], v[220:223], v[6:9]
	v_mfma_f32_16x16x32_bf16 v[2:5], v[236:239], v[220:223], v[2:5]
	v_mfma_f32_16x16x32_bf16 v[54:57], v[232:235], v[200:203], v[54:57]
	v_mfma_f32_16x16x32_bf16 v[50:53], v[240:243], v[200:203], v[50:53]
	v_mfma_f32_16x16x32_bf16 v[38:41], v[232:235], v[208:211], v[38:41]
	v_mfma_f32_16x16x32_bf16 v[34:37], v[240:243], v[208:211], v[34:37]
	v_mfma_f32_16x16x32_bf16 v[22:25], v[232:235], v[216:219], v[22:25]
	v_mfma_f32_16x16x32_bf16 v[18:21], v[240:243], v[216:219], v[18:21]
	v_mfma_f32_16x16x32_bf16 v[6:9], v[232:235], v[224:227], v[6:9]
	v_mfma_f32_16x16x32_bf16 v[2:5], v[240:243], v[224:227], v[2:5]
	s_setprio 0
	s_add_i32 s62, s62, 2
	s_add_u32 s46, s46, 0x100
	s_addc_u32 s47, s47, 0
	s_add_u32 s52, s52, 0x100
	s_addc_u32 s53, s53, 0
	s_cmp_gt_u32 s62, 13
	s_barrier
	s_cbranch_scc0 .LBB0_1230
	s_cmp_eq_u32 s42, 16
	s_cbranch_scc1 .Lbf_orig_mlin
;   __device__ __forceinline__ void operator()(const f32x4 (&acc)[2][2][4][2], const pg8::Unit& u, int wr, int wc, int fr, int fq) const {
; #pragma unroll
;     for (int ai = 0; ai < 2; ++ai)
; #pragma unroll
;       for (int m = 0; m < 4; ++m) { const int row = u.pm * 256 + ai * 128 + wr * 64 + m * 16 + fr;
; #pragma unroll
;         for (int bj = 0; bj < 2; ++bj)
; #pragma unroll
;           for (int n = 0; n < 2; ++n) f(row, u.pn * 256 + bj * 128 + wc * 32 + n * 16 + 4 * fq, acc[ai][bj][m][n]); }
;   }
	s_movk_i32 s7, 0x2000
	v_bfe_u32 v178, v168, 4, 1
	v_mul_u32_u24_e32 v178, 24, v178
	v_lshl_add_u32 v178, v152, 1, v178
	v_mad_u32_u24 v178, v147, s7, v178
	s_lshl_b32 s50, s58, 1
	v_add_u32_e32 v178, s50, v178
	s_lshl_b32 s48, s44, 21
	s_lshl_b32 s50, s42, 9
	s_add_i32 s48, s48, s50
	s_add_u32 s48, s26, s48
	s_addc_u32 s49, s27, 0
	v_readlane_b32 s64, v254, 56
	s_movk_i32 s65, 0x100
	v_cvt_pk_bf16_f32 v125, v124, v125
	v_cvt_pk_bf16_f32 v124, v122, v123
	v_cvt_pk_bf16_f32 v122, v126, v127
	v_cvt_pk_bf16_f32 v123, v128, v129
	v_cvt_pk_bf16_f32 v117, v116, v117
	v_cvt_pk_bf16_f32 v116, v114, v115
	v_cvt_pk_bf16_f32 v114, v118, v119
	v_cvt_pk_bf16_f32 v115, v120, v121
	v_permlane16_swap_b32_e32 v122, v124
	v_permlane16_swap_b32_e32 v123, v125
	v_permlane16_swap_b32_e32 v114, v116
	v_permlane16_swap_b32_e32 v115, v117
	global_store_dwordx4 v178, v[122:125], s[48:49]
	global_store_dwordx4 v178, v[114:117], s[48:49] offset:256
	s_add_u32 s48, s48, 0x20000
	s_addc_u32 s49, s49, 0
	v_cvt_pk_bf16_f32 v109, v108, v109
	v_cvt_pk_bf16_f32 v108, v106, v107
	v_cvt_pk_bf16_f32 v106, v110, v111
	v_cvt_pk_bf16_f32 v107, v112, v113
	v_cvt_pk_bf16_f32 v101, v100, v101
	v_cvt_pk_bf16_f32 v100, v98, v99
	v_cvt_pk_bf16_f32 v98, v102, v103
	v_cvt_pk_bf16_f32 v99, v104, v105
	v_permlane16_swap_b32_e32 v106, v108
	v_permlane16_swap_b32_e32 v107, v109
	v_permlane16_swap_b32_e32 v98, v100
	v_permlane16_swap_b32_e32 v99, v101
	global_store_dwordx4 v178, v[106:109], s[48:49]
	global_store_dwordx4 v178, v[98:101], s[48:49] offset:256
	s_add_u32 s48, s48, 0x20000
	s_addc_u32 s49, s49, 0
	v_cvt_pk_bf16_f32 v93, v92, v93
	v_cvt_pk_bf16_f32 v92, v90, v91
	v_cvt_pk_bf16_f32 v90, v94, v95
	v_cvt_pk_bf16_f32 v91, v96, v97
	v_cvt_pk_bf16_f32 v85, v84, v85
	v_cvt_pk_bf16_f32 v84, v82, v83
	v_cvt_pk_bf16_f32 v82, v86, v87
	v_cvt_pk_bf16_f32 v83, v88, v89
	v_permlane16_swap_b32_e32 v90, v92
	v_permlane16_swap_b32_e32 v91, v93
	v_permlane16_swap_b32_e32 v82, v84
	v_permlane16_swap_b32_e32 v83, v85
	global_store_dwordx4 v178, v[90:93], s[48:49]
	global_store_dwordx4 v178, v[82:85], s[48:49] offset:256
	s_add_u32 s48, s48, 0x20000
	s_addc_u32 s49, s49, 0
	v_cvt_pk_bf16_f32 v77, v76, v77
	v_cvt_pk_bf16_f32 v76, v74, v75
	v_cvt_pk_bf16_f32 v74, v78, v79
	v_cvt_pk_bf16_f32 v75, v80, v81
	v_cvt_pk_bf16_f32 v69, v68, v69
	v_cvt_pk_bf16_f32 v68, v66, v67
	v_cvt_pk_bf16_f32 v66, v70, v71
	v_cvt_pk_bf16_f32 v67, v72, v73
	v_permlane16_swap_b32_e32 v74, v76
	v_permlane16_swap_b32_e32 v75, v77
	v_permlane16_swap_b32_e32 v66, v68
	v_permlane16_swap_b32_e32 v67, v69
	global_store_dwordx4 v178, v[74:77], s[48:49]
	global_store_dwordx4 v178, v[66:69], s[48:49] offset:256
	s_add_u32 s48, s48, 0xa0000
	s_addc_u32 s49, s49, 0
	v_cvt_pk_bf16_f32 v61, v60, v61
	v_cvt_pk_bf16_f32 v60, v58, v59
	v_cvt_pk_bf16_f32 v58, v62, v63
	v_cvt_pk_bf16_f32 v59, v64, v65
	v_cvt_pk_bf16_f32 v53, v52, v53
	v_cvt_pk_bf16_f32 v52, v50, v51
	v_cvt_pk_bf16_f32 v50, v54, v55
	v_cvt_pk_bf16_f32 v51, v56, v57
	v_permlane16_swap_b32_e32 v58, v60
	v_permlane16_swap_b32_e32 v59, v61
	v_permlane16_swap_b32_e32 v50, v52
	v_permlane16_swap_b32_e32 v51, v53
	global_store_dwordx4 v178, v[58:61], s[48:49]
	global_store_dwordx4 v178, v[50:53], s[48:49] offset:256
	s_add_u32 s48, s48, 0x20000
	s_addc_u32 s49, s49, 0
	v_cvt_pk_bf16_f32 v45, v44, v45
	v_cvt_pk_bf16_f32 v44, v42, v43
	v_cvt_pk_bf16_f32 v42, v46, v47
	v_cvt_pk_bf16_f32 v43, v48, v49
	v_cvt_pk_bf16_f32 v37, v36, v37
	v_cvt_pk_bf16_f32 v36, v34, v35
	v_cvt_pk_bf16_f32 v34, v38, v39
	v_cvt_pk_bf16_f32 v35, v40, v41
	v_permlane16_swap_b32_e32 v42, v44
	v_permlane16_swap_b32_e32 v43, v45
	v_permlane16_swap_b32_e32 v34, v36
	v_permlane16_swap_b32_e32 v35, v37
	global_store_dwordx4 v178, v[42:45], s[48:49]
	global_store_dwordx4 v178, v[34:37], s[48:49] offset:256
	s_add_u32 s48, s48, 0x20000
	s_addc_u32 s49, s49, 0
	v_cvt_pk_bf16_f32 v29, v28, v29
	v_cvt_pk_bf16_f32 v28, v26, v27
	v_cvt_pk_bf16_f32 v26, v30, v31
	v_cvt_pk_bf16_f32 v27, v32, v33
	v_cvt_pk_bf16_f32 v21, v20, v21
	v_cvt_pk_bf16_f32 v20, v18, v19
	v_cvt_pk_bf16_f32 v18, v22, v23
	v_cvt_pk_bf16_f32 v19, v24, v25
	v_permlane16_swap_b32_e32 v26, v28
	v_permlane16_swap_b32_e32 v27, v29
	v_permlane16_swap_b32_e32 v18, v20
	v_permlane16_swap_b32_e32 v19, v21
	global_store_dwordx4 v178, v[26:29], s[48:49]
	global_store_dwordx4 v178, v[18:21], s[48:49] offset:256
	s_add_u32 s48, s48, 0x20000
	s_addc_u32 s49, s49, 0
	v_cvt_pk_bf16_f32 v13, v12, v13
	v_cvt_pk_bf16_f32 v12, v10, v11
	v_cvt_pk_bf16_f32 v10, v14, v15
	v_cvt_pk_bf16_f32 v11, v16, v17
	v_cvt_pk_bf16_f32 v5, v4, v5
	v_cvt_pk_bf16_f32 v4, v2, v3
	v_cvt_pk_bf16_f32 v2, v6, v7
	v_cvt_pk_bf16_f32 v3, v8, v9
	v_permlane16_swap_b32_e32 v10, v12
	v_permlane16_swap_b32_e32 v11, v13
	v_permlane16_swap_b32_e32 v2, v4
	v_permlane16_swap_b32_e32 v3, v5
	global_store_dwordx4 v178, v[10:13], s[48:49]
	global_store_dwordx4 v178, v[2:5], s[48:49] offset:256
	s_branch .LBB0_1222
.Lbf_orig_mlin:
	s_lshl_b32 s7, s42, 8
	v_lshl_add_u32 v160, s44, 8, v147
	s_or_b32 s50, s7, s58
	v_ashrrev_i32_e32 v161, 31, v160
	v_or_b32_e32 v158, s50, v152
	s_movk_i32 s7, 0xfff
	v_lshlrev_b64 v[162:163], 7, v[160:161]
	v_cmp_lt_i32_e64 s[44:45], s7, v158
	s_and_saveexec_b64 s[42:43], s[44:45]
	s_xor_b64 s[42:43], exec, s[42:43]
	s_cbranch_execz .LBB0_1234
	s_cmpk_gt_u32 s50, 0x101f
	s_cbranch_scc1 .LBB0_1234
	v_lshl_add_u64 v[164:165], s[26:27], 0, v[162:163]
	v_mov_b32_e32 v159, v1
	v_lshl_add_u64 v[164:165], v[158:159], 2, v[164:165]
	v_add_co_u32_e32 v164, vcc, 0x103fc000, v164
	s_nop 1
	v_addc_co_u32_e32 v165, vcc, 0, v165, vcc
	global_store_dwordx4 v[164:165], v[126:129], off

; #define PG8_STAGE(bufoff, gbase, voff) do { _Pragma("unroll") for (int _i = 0; _i < 2; ++_i) \
;     __builtin_amdgcn_global_load_lds((const unsigned*)((const char*)(gbase) + (voff)[_i]), (PG8_LAS unsigned*)(lds + (bufoff) + ldsw + _i * 8192), 16, 0, 0); } while (0)
; #define PG8_WAIT_V(n) asm volatile("s_waitcnt vmcnt(" #n ")" ::: "memory")
; #define PG8_BAR __builtin_amdgcn_s_barrier()
;   __device__ bool next(int i, Unit& u) const {
;     const long L = (long)i * G + c; if (L >= nwg) return false;
;     int wgid = (int)L; { const int q = nwg / NXCD, r = nwg % NXCD, xcd = wgid % NXCD, off = wgid / NXCD; wgid = (xcd < r ? xcd * (q + 1) : r * (q + 1) + (xcd - r) * q) + off; }
;     const int nig = WGM * nN, gid = wgid / nig, fm = gid * WGM, gsz = (nM - fm) < WGM ? (nM - fm) : WGM;
;     u.pm = fm + ((wgid % nig) % gsz); u.pn = (wgid % nig) / gsz; return true;
;   }
; template <class Epi>
; __device__ __forceinline__ void gemm_phase(PG8_LAS unsigned char* lds, const Gemm g, const StaticOrder& S, const Epi& E) {
;     ...
;   const char* cA = (const char*)g.A + (size_t)cur.pm * tstep; const char* cB = (const char*)g.Bt + (size_t)cur.pn * tstep;
;   PG8_STAGE(PG8_SB(0, 0), cB, voffB); PG8_STAGE(PG8_SA(0, 0), cA, voffA); PG8_STAGE(PG8_SB(0, 1), cB + hstep, voffB); PG8_STAGE(PG8_SA(0, 1), cA + hstep, voffA);
;   if (wr == 1) PG8_BAR;
;   PG8_WAIT_V(4); PG8_BAR;
;   PG8_STAGE(PG8_SB(1, 0), cB + kstep, voffB); PG8_STAGE(PG8_SA(1, 0), cA + kstep, voffA); PG8_STAGE(PG8_SB(1, 1), cB + hstep + kstep, voffB);
;   PG8_WAIT_V(6); PG8_BAR;
.LBB0_1395:
	s_and_b64 vcc, exec, s[6:7]
	s_cbranch_vccz .LBB0_1478
	v_readlane_b32 s6, v251, 10
	v_readlane_b32 s7, v251, 11
	s_waitcnt vmcnt(0)
	v_mov_b32_e32 v18, v168
	s_andn2_b64 vcc, exec, s[6:7]
	v_cndmask_b32_e64 v0, 0, 1, s[6:7]
	v_cmp_ne_u32_e64 s[40:41], 1, v0
	v_readfirstlane_b32 s19, v18
	s_cbranch_vccnz .LBB0_1398
	v_readlane_b32 s57, v253, 9
	v_readlane_b32 s58, v252, 54
	s_and_b64 vcc, exec, s[12:13]
	s_cbranch_vccz .Lcs_e0
	s_and_b32 s57, s84, 7
	s_lshl_b32 s57, s57, 6
	s_lshr_b32 s58, s84, 3
	s_add_i32 s57, s57, s58
	s_lshr_b32 s58, s57, 5
	s_lshl_b32 s58, s58, 3
	s_and_b32 s57, s57, 31
	s_and_b32 vcc_lo, s57, 7
	s_add_i32 s58, s58, vcc_lo
	s_lshr_b32 s57, s57, 3
	s_cmp_ge_u32 s58, 64
	s_cselect_b32 vcc_lo, 2, 1
	s_add_i32 s58, s58, vcc_lo
.Lcs_e0:
.LBB0_1398:
	s_and_b64 vcc, exec, s[40:41]
	s_cbranch_vccnz .LBB0_1478
	v_ashrrev_i32_e32 v0, 31, v18
	v_lshrrev_b32_e32 v0, 26, v0
	v_add_u32_e32 v0, v18, v0
	v_ashrrev_i32_e32 v10, 6, v0
	v_bfe_i32 v0, v18, 27, 1
	s_waitcnt lgkmcnt(0)
	v_lshlrev_b32_e32 v2, 4, v18
	v_lshrrev_b32_e32 v0, 22, v0
	v_add_u32_e32 v0, v2, v0
	v_and_b32_e32 v0, 0xfffffc00, v0
	v_sub_u32_e32 v0, v2, v0
	v_lshrrev_b32_e32 v3, 4, v0
	v_bitop3_b32 v3, v3, v0, 32 bitop3:0x6c
	v_ashrrev_i32_e32 v0, 31, v0
	v_lshrrev_b32_e32 v0, 26, v0
	v_lshlrev_b32_e32 v4, 3, v10
	v_add_u32_e32 v0, v3, v0
	v_and_b32_e32 v4, 0xfffff0, v4
	v_ashrrev_i32_e32 v12, 6, v0
	v_add_u32_e32 v0, v12, v4
	v_lshlrev_b32_e32 v4, 5, v10
	v_and_b32_e32 v11, 32, v4
	v_mul_i32_i24_e32 v4, 64, v12
	v_sub_u32_e32 v3, v3, v4
	v_ashrrev_i16_sdwa v3, v172, sext(v3) dst_sel:DWORD dst_unused:UNUSED_PAD src0_sel:DWORD src1_sel:BYTE_0
	v_add_u32_e32 v2, 0x2000, v2
	v_bfe_i32 v13, v3, 0, 16
	v_ashrrev_i32_e32 v3, 31, v2
	v_lshrrev_b32_e32 v3, 22, v3
	v_add_u32_e32 v3, v2, v3
	v_ashrrev_i32_e32 v14, 10, v3
	v_mul_i32_i24_e32 v3, 0x400, v14
	v_sub_u32_e32 v2, v2, v3
	v_lshrrev_b32_e32 v3, 4, v2
	v_bitop3_b32 v2, v3, v2, 32 bitop3:0x6c
	v_ashrrev_i32_e32 v4, 31, v2
	v_lshrrev_b32_e32 v4, 26, v4
	v_add_u32_e32 v4, v2, v4
	s_ashr_i32 s9, s19, 6
	s_ashr_i32 s8, s19, 8
	v_lshlrev_b32_e32 v3, 3, v14
	v_ashrrev_i32_e32 v16, 6, v4
	v_and_b32_e32 v4, 0xc0, v4
	s_lshl_b32 s28, s9, 10
	s_mul_i32 s11, s57, 0xa0000
	v_readlane_b32 s30, v251, 41
	v_mul_lo_u32 v0, v0, s17
	v_and_b32_e32 v3, 0xfffff0, v3
	v_sub_u32_e32 v2, v2, v4
	s_mul_hi_i32 s10, s57, 0xa0000
	s_add_u32 s46, s30, s11
	v_readlane_b32 s11, v251, 42
	v_or_b32_e32 v0, v0, v11
	v_add_u32_e32 v3, v16, v3
	v_lshlrev_b32_e32 v5, 5, v14
	v_ashrrev_i16_sdwa v2, v172, sext(v2) dst_sel:DWORD dst_unused:UNUSED_PAD src0_sel:DWORD src1_sel:BYTE_0
	s_addc_u32 s47, s11, s10
	s_add_i32 s48, s28, 0
	v_add_lshl_u32 v0, v0, v13, 1
	v_and_b32_e32 v15, 32, v5
	v_bfe_i32 v17, v2, 0, 16
	v_mul_lo_u32 v2, v3, s17
	s_add_i32 m0, s48, 0x10000
	v_or_b32_e32 v2, v2, v15
	s_mul_i32 s7, s58, 0xa0000
	global_load_lds_dwordx4 v0, s[46:47]
	s_add_i32 m0, s48, 0x12000
	v_add_lshl_u32 v148, v2, v17, 1
	s_mul_hi_i32 s6, s58, 0xa0000
	s_add_u32 s30, s26, s7
	global_load_lds_dwordx4 v148, s[46:47]
	s_addc_u32 s31, s27, s6
	s_mov_b32 m0, s48
	s_add_i32 s49, s48, 0x2000
	global_load_lds_dwordx4 v0, s[30:31]
	s_mov_b32 m0, s49
	s_add_u32 s6, s46, 0x50000
	global_load_lds_dwordx4 v148, s[30:31]
	s_addc_u32 s7, s47, 0
	s_add_i32 m0, s48, 0x14000
	v_mov_b32_e32 v149, v1
	global_load_lds_dwordx4 v0, s[6:7]
	s_add_i32 m0, s48, 0x16000
	v_lshl_add_u64 v[8:9], s[46:47], 0, v[0:1]
	global_load_lds_dwordx4 v148, s[6:7]
	s_add_u32 s6, s30, 0x50000
	s_addc_u32 s7, s31, 0
	s_add_i32 s50, s48, 0x4000
	s_mov_b32 m0, s50
	s_add_i32 s51, s48, 0x6000
	global_load_lds_dwordx4 v0, s[6:7]
	s_mov_b32 m0, s51
	v_lshl_add_u64 v[6:7], s[46:47], 0, v[148:149]
	global_load_lds_dwordx4 v148, s[6:7]
	v_lshl_add_u64 v[4:5], s[30:31], 0, v[0:1]
	s_cmp_lg_u32 s8, 1
	v_lshl_add_u64 v[2:3], s[30:31], 0, v[148:149]
	s_cbranch_scc1 .LBB0_1401
	s_barrier

;   __device__ bool next(int i, Unit& u) const {
;     const long L = (long)i * G + c; if (L >= nwg) return false;
;     int wgid = (int)L; { const int q = nwg / NXCD, r = nwg % NXCD, xcd = wgid % NXCD, off = wgid / NXCD; wgid = (xcd < r ? xcd * (q + 1) : r * (q + 1) + (xcd - r) * q) + off; }
;     const int nig = WGM * nN, gid = wgid / nig, fm = gid * WGM, gsz = (nM - fm) < WGM ? (nM - fm) : WGM;
;     u.pm = fm + ((wgid % nig) % gsz); u.pn = (wgid % nig) / gsz; return true;
;   }
; template <class Epi>
; __device__ __forceinline__ void gemm_phase(PG8_LAS unsigned char* lds, const Gemm g, const StaticOrder& S, const Epi& E) {
;     ...
;     const bool has_next = S.next(ui + 1, nxt);
;     const char* nA = has_next ? (const char*)g.A + (size_t)nxt.pm * tstep : cA; const char* nB = has_next ? (const char*)g.Bt + (size_t)nxt.pn * tstep : cB;
.LBB0_1403:
	s_add_i32 s54, s54, 1
	v_readlane_b32 s8, v251, 12
	s_mul_i32 s8, s54, s8
	s_mul_hi_u32 s9, s54, s96
	s_add_i32 s9, s9, s8
	s_mul_i32 s8, s54, s96
	s_add_u32 s8, s8, s84
	s_addc_u32 s9, s9, s85
	v_cmp_gt_i64_e64 s[40:41], s[8:9], v[130:131]
	v_cmp_lt_i64_e64 s[42:43], s[8:9], v[132:133]
	s_and_b64 vcc, exec, s[12:13]
	s_cbranch_vccz .Lcs_h0
	s_cmp_gt_u32 s8, 0x1ff
	s_cselect_b64 s[40:41], exec, 0
	s_cselect_b64 s[42:43], 0, exec
	s_cbranch_scc1 .LBB0_1405
	s_and_b32 s9, s8, 7
	s_lshl_b32 s9, s9, 6
	s_lshr_b32 s10, s8, 3
	s_add_i32 s9, s9, s10
	s_lshr_b32 s10, s9, 5
	s_lshl_b32 s10, s10, 3
	s_and_b32 s9, s9, 31
	s_and_b32 s11, s9, 7
	s_add_i32 s56, s10, s11
	s_lshr_b32 s55, s9, 3
	s_cmp_ge_u32 s56, 64
	s_cselect_b32 s11, 2, 1
	s_add_i32 s56, s56, s11
	s_branch .LBB0_1405
.Lcs_h0:
	s_and_b64 vcc, exec, s[40:41]
	s_cbranch_vccnz .LBB0_1405
	s_ashr_i32 s9, s8, 31
	s_lshr_b32 s9, s9, 29
	s_add_i32 s9, s8, s9
	s_ashr_i32 s10, s9, 3
	s_and_b32 s9, s9, -8
	s_sub_i32 s8, s8, s9
	s_cmp_lt_i32 s8, 0
	s_movk_i32 s9, 0x42
	s_cselect_b32 s9, s9, 0x41
	s_mul_i32 s8, s9, s8
	s_add_i32 s8, s8, s10
	s_ashr_i32 s9, s8, 31
	s_lshr_b32 s9, s9, 27
	s_add_i32 s9, s8, s9
	s_ashr_i32 s10, s9, 5
	s_lshl_b32 s10, s10, 3
	s_sub_i32 s11, 0x82, s10
	s_min_i32 s11, s11, 8
	s_abs_i32 s44, s11
	v_cvt_f32_u32_e32 v2, s44
	s_sub_i32 s55, 0, s44
	s_andn2_b32 s9, s9, 31
	s_sub_i32 s8, s8, s9
	v_rcp_iflag_f32_e32 v2, v2
	s_abs_i32 s9, s8
	s_xor_b32 s45, s8, s11
	s_ashr_i32 s45, s45, 31
	v_mul_f32_e32 v2, 0x4f7ffffe, v2
	v_cvt_u32_f32_e32 v2, v2
	s_nop 0
	v_readfirstlane_b32 s56, v2
	s_mul_i32 s55, s55, s56
	s_mul_hi_u32 s55, s56, s55
	s_add_i32 s56, s56, s55
	s_mul_hi_u32 s55, s9, s56
	s_mul_i32 s56, s55, s44
	s_sub_i32 s9, s9, s56
	s_add_i32 s59, s55, 1
	s_sub_i32 s56, s9, s44
	s_cmp_ge_u32 s9, s44
	s_cselect_b32 s55, s59, s55
	s_cselect_b32 s9, s56, s9
	s_add_i32 s56, s55, 1
	s_cmp_ge_u32 s9, s44
	s_cselect_b32 s9, s56, s55
	s_xor_b32 s9, s9, s45
	s_sub_i32 s55, s9, s45
	s_mul_i32 s9, s55, s11
	s_sub_i32 s8, s8, s9
	s_add_i32 s56, s8, s10

; template <class Epi>
; __device__ __forceinline__ void gemm_phase(PG8_LAS unsigned char* lds, const Gemm g, const StaticOrder& S, const Epi& E) {
;     ...
;     E(acc, cur, wr, wc, fr, fq);
;     if (!has_next) break;
; #pragma unroll
;     for (int a = 0; a < 2; ++a)
; #pragma unroll
;       for (int b = 0; b < 2; ++b)
; #pragma unroll
;         for (int m = 0; m < 4; ++m)
; #pragma unroll
;           for (int n = 0; n < 2; ++n) acc[a][b][m][n] = (f32x4){0.f, 0.f, 0.f, 0.f};
;     cur = nxt; cA = nA; cB = nB; ++ui;
.Llin_latch:
	s_and_b64 vcc, exec, s[40:41]
	s_mov_b32 s30, s6
	s_mov_b32 s42, s8
	s_mov_b64 s[46:47], s[12:13]
	s_mov_b64 s[44:45], s[10:11]
	s_cbranch_vccnz .LBB0_1722

; #define PG8_STAGE(bufoff, gbase, voff) do { _Pragma("unroll") for (int _i = 0; _i < 2; ++_i) \
;     __builtin_amdgcn_global_load_lds((const unsigned*)((const char*)(gbase) + (voff)[_i]), (PG8_LAS unsigned*)(lds + (bufoff) + ldsw + _i * 8192), 16, 0, 0); } while (0)
; #define PG8_LDA(dst, b, h) do { _Pragma("unroll") for (int m = 0; m < 4; ++m) _Pragma("unroll") for (int k = 0; k < 2; ++k) dst[m][k] = *(const PG8_LAS bf16x8*)(lds + PG8_SA(b, h) + aoff + m * 2048 + k * 1024); } while (0)
; #define PG8_LDB(dst, b, h) do { _Pragma("unroll") for (int n = 0; n < 2; ++n) _Pragma("unroll") for (int k = 0; k < 2; ++k) dst[n][k] = *(const PG8_LAS bf16x8*)(lds + PG8_SB(b, h) + boff + n * 2048 + k * 1024); } while (0)
; #define PG8_BAR __builtin_amdgcn_s_barrier()
; template <class Epi>
; __device__ __forceinline__ void gemm_phase(PG8_LAS unsigned char* lds, const Gemm g, const StaticOrder& S, const Epi& E) {
;     ...
;     for (int t = 0; t < nt; t += 2) {
;       const bool last = (t == nt - 2);
;       const char* a1 = cA + (size_t)(t + 1) * kstep;
;       const char* a2 = last ? nA : cA + (size_t)(t + 2) * kstep; const char* b2 = last ? nB : cB + (size_t)(t + 2) * kstep;
;       const char* a3 = a2 + kstep; const char* b3 = b2 + kstep;
;       PG8_LDB(B0, 0, 0); PG8_SCHED; PG8_LDA(At, 0, 0); PG8_STAGE(PG8_SA(1, 1), a1 + hstep, voffA);
;       PG8_WAIT_L(8); PG8_BAR; PG8_WAIT_L(0); PG8_MMA(0, 0, At, B0); PG8_BAR; PG8_SCHED;
;       PG8_LDB(B1, 0, 1); PG8_STAGE(PG8_SB(0, 0), b2, voffB);
;       PG8_BAR; PG8_WAIT_L(0); PG8_MMA(0, 1, At, B1); PG8_BAR;
;       PG8_LDA(At, 0, 1); PG8_STAGE(PG8_SA(0, 0), a2, voffA);
;       PG8_BAR; PG8_WAIT_L(0); PG8_MMA(1, 0, At, B0); PG8_BAR; PG8_SCHED;
;       PG8_STAGE(PG8_SB(0, 1), b2 + hstep, voffB);
;       PG8_WAIT_V(6); PG8_BAR; PG8_MMA(1, 1, At, B1); PG8_BAR;
;       PG8_LDB(B0, 1, 0); PG8_SCHED; PG8_LDA(At, 1, 0); PG8_STAGE(PG8_SA(0, 1), a2 + hstep, voffA);
;       PG8_WAIT_L(8); PG8_BAR; PG8_WAIT_L(0); PG8_MMA(0, 0, At, B0); PG8_BAR; PG8_SCHED;
;       PG8_LDB(B1, 1, 1); PG8_STAGE(PG8_SB(1, 0), b3, voffB);
;       PG8_BAR; PG8_WAIT_L(0); PG8_MMA(0, 1, At, B1); PG8_BAR;
;       PG8_LDA(At, 1, 1); PG8_STAGE(PG8_SA(1, 0), a3, voffA);
;       PG8_BAR; PG8_WAIT_L(0); PG8_MMA(1, 0, At, B0); PG8_BAR; PG8_SCHED;
;       PG8_STAGE(PG8_SB(1, 1), b3 + hstep, voffB);
;       PG8_WAIT_V(6); PG8_BAR; PG8_MMA(1, 1, At, B1); PG8_BAR;
;     }
.LBB0_1593:
	s_add_u32 s46, s44, 0xfffc0080
	s_addc_u32 s47, s45, -1
	s_add_i32 s59, 0, 0x10000
	v_add_u32_e32 v0, s59, v164
	ds_read_b128 v[156:159], v0
	ds_read_b128 v[160:163], v0 offset:1024
	ds_read_b128 v[188:191], v0 offset:2048
	ds_read_b128 v[192:195], v0 offset:3072
	s_cmp_eq_u32 s58, 12
	s_cselect_b32 s49, s9, s47
	s_cselect_b32 s48, s31, s46
	s_cselect_b32 s47, s7, s57
	s_cselect_b32 s46, s43, s56
	v_lshl_add_u64 v[228:229], s[44:45], 0, v[152:153]
	s_add_i32 m0, s28, 0xc000
	ds_read_b128 v[196:199], v166
	ds_read_b128 v[200:203], v166 offset:1024
	ds_read_b128 v[204:207], v166 offset:2048
	ds_read_b128 v[208:211], v166 offset:3072
	ds_read_b128 v[212:215], v166 offset:4096
	ds_read_b128 v[216:219], v166 offset:5120
	ds_read_b128 v[220:223], v166 offset:6144
	ds_read_b128 v[224:227], v166 offset:7168
	global_load_lds_dwordx4 v[228:229], off
	v_lshl_add_u64 v[228:229], s[44:45], 0, v[154:155]
	s_add_i32 m0, s28, 0xe000
	s_nop 0
	global_load_lds_dwordx4 v[228:229], off
	s_waitcnt lgkmcnt(8)
	s_barrier
	s_waitcnt lgkmcnt(0)
	s_setprio 1
	s_waitcnt lgkmcnt(0)
	v_mfma_f32_16x16x32_bf16 v[126:129], v[156:159], v[196:199], v[126:129]
	v_mfma_f32_16x16x32_bf16 v[122:125], v[188:191], v[196:199], v[122:125]
	v_mfma_f32_16x16x32_bf16 v[110:113], v[156:159], v[204:207], v[110:113]
	v_mfma_f32_16x16x32_bf16 v[106:109], v[188:191], v[204:207], v[106:109]
	v_mfma_f32_16x16x32_bf16 v[94:97], v[156:159], v[212:215], v[94:97]
	v_mfma_f32_16x16x32_bf16 v[90:93], v[188:191], v[212:215], v[90:93]
	v_mfma_f32_16x16x32_bf16 v[78:81], v[156:159], v[220:223], v[78:81]
	v_mfma_f32_16x16x32_bf16 v[74:77], v[188:191], v[220:223], v[74:77]
	v_mfma_f32_16x16x32_bf16 v[126:129], v[160:163], v[200:203], v[126:129]
	v_mfma_f32_16x16x32_bf16 v[122:125], v[192:195], v[200:203], v[122:125]
	v_mfma_f32_16x16x32_bf16 v[110:113], v[160:163], v[208:211], v[110:113]
	v_mfma_f32_16x16x32_bf16 v[106:109], v[192:195], v[208:211], v[106:109]
	v_mfma_f32_16x16x32_bf16 v[94:97], v[160:163], v[216:219], v[94:97]
	v_mfma_f32_16x16x32_bf16 v[90:93], v[192:195], v[216:219], v[90:93]
	v_mfma_f32_16x16x32_bf16 v[78:81], v[160:163], v[224:227], v[78:81]
	v_mfma_f32_16x16x32_bf16 v[74:77], v[192:195], v[224:227], v[74:77]
	s_setprio 0
	s_barrier
	s_add_i32 s62, 0, 0x14000
	s_add_i32 s59, s59, s19
	v_add_u32_e32 v0, s62, v164
	v_lshl_add_u64 v[244:245], s[46:47], 0, v[148:149]
	s_mov_b32 m0, s59
	ds_read_b128 v[228:231], v0
	ds_read_b128 v[232:235], v0 offset:1024
	ds_read_b128 v[236:239], v0 offset:2048
	ds_read_b128 v[240:243], v0 offset:3072
	global_load_lds_dwordx4 v[244:245], off
	v_lshl_add_u64 v[246:247], s[46:47], 0, v[150:151]
	s_add_i32 m0, s59, 0x2000
	s_nop 0
	global_load_lds_dwordx4 v[246:247], off
	s_barrier
	s_waitcnt lgkmcnt(0)
	s_setprio 1
	s_waitcnt lgkmcnt(0)
	v_mfma_f32_16x16x32_bf16 v[118:121], v[228:231], v[196:199], v[118:121]
	v_mfma_f32_16x16x32_bf16 v[114:117], v[236:239], v[196:199], v[114:117]
	v_mfma_f32_16x16x32_bf16 v[102:105], v[228:231], v[204:207], v[102:105]
	v_mfma_f32_16x16x32_bf16 v[98:101], v[236:239], v[204:207], v[98:101]
	v_mfma_f32_16x16x32_bf16 v[86:89], v[228:231], v[212:215], v[86:89]
	v_mfma_f32_16x16x32_bf16 v[82:85], v[236:239], v[212:215], v[82:85]
	v_mfma_f32_16x16x32_bf16 v[70:73], v[228:231], v[220:223], v[70:73]
	v_mfma_f32_16x16x32_bf16 v[66:69], v[236:239], v[220:223], v[66:69]
	v_mfma_f32_16x16x32_bf16 v[118:121], v[232:235], v[200:203], v[118:121]
	v_mfma_f32_16x16x32_bf16 v[114:117], v[240:243], v[200:203], v[114:117]
	v_mfma_f32_16x16x32_bf16 v[102:105], v[232:235], v[208:211], v[102:105]
	v_mfma_f32_16x16x32_bf16 v[98:101], v[240:243], v[208:211], v[98:101]
	v_mfma_f32_16x16x32_bf16 v[86:89], v[232:235], v[216:219], v[86:89]
	v_mfma_f32_16x16x32_bf16 v[82:85], v[240:243], v[216:219], v[82:85]
	v_mfma_f32_16x16x32_bf16 v[70:73], v[232:235], v[224:227], v[70:73]
	v_mfma_f32_16x16x32_bf16 v[66:69], v[240:243], v[224:227], v[66:69]
	s_setprio 0
	s_mov_b32 m0, s28
	v_lshl_add_u64 v[248:249], s[48:49], 0, v[148:149]
	s_barrier
	ds_read_b128 v[196:199], v166 offset:16384
	ds_read_b128 v[200:203], v166 offset:17408
	ds_read_b128 v[204:207], v166 offset:18432
	ds_read_b128 v[208:211], v166 offset:19456
	ds_read_b128 v[212:215], v166 offset:20480
	ds_read_b128 v[216:219], v166 offset:21504
	ds_read_b128 v[220:223], v166 offset:22528
	ds_read_b128 v[224:227], v166 offset:23552
	global_load_lds_dwordx4 v[248:249], off
	v_lshl_add_u64 v[178:179], s[48:49], 0, v[150:151]
	s_mov_b32 m0, s50
	s_nop 0
	global_load_lds_dwordx4 v[178:179], off
	s_barrier
	s_waitcnt lgkmcnt(0)
	s_setprio 1
	s_waitcnt lgkmcnt(0)
	v_mfma_f32_16x16x32_bf16 v[62:65], v[156:159], v[196:199], v[62:65]
	v_mfma_f32_16x16x32_bf16 v[58:61], v[188:191], v[196:199], v[58:61]
	v_mfma_f32_16x16x32_bf16 v[46:49], v[156:159], v[204:207], v[46:49]
	v_mfma_f32_16x16x32_bf16 v[42:45], v[188:191], v[204:207], v[42:45]
	v_mfma_f32_16x16x32_bf16 v[30:33], v[156:159], v[212:215], v[30:33]
	v_mfma_f32_16x16x32_bf16 v[26:29], v[188:191], v[212:215], v[26:29]
	v_mfma_f32_16x16x32_bf16 v[14:17], v[156:159], v[220:223], v[14:17]
	v_mfma_f32_16x16x32_bf16 v[10:13], v[188:191], v[220:223], v[10:13]
	v_mfma_f32_16x16x32_bf16 v[62:65], v[160:163], v[200:203], v[62:65]
	v_mfma_f32_16x16x32_bf16 v[58:61], v[192:195], v[200:203], v[58:61]
	v_mfma_f32_16x16x32_bf16 v[46:49], v[160:163], v[208:211], v[46:49]
	v_mfma_f32_16x16x32_bf16 v[42:45], v[192:195], v[208:211], v[42:45]
	v_mfma_f32_16x16x32_bf16 v[30:33], v[160:163], v[216:219], v[30:33]
	v_mfma_f32_16x16x32_bf16 v[26:29], v[192:195], v[216:219], v[26:29]
	v_mfma_f32_16x16x32_bf16 v[14:17], v[160:163], v[224:227], v[14:17]
	v_mfma_f32_16x16x32_bf16 v[10:13], v[192:195], v[224:227], v[10:13]
	s_setprio 0
	s_barrier
; #define PG8_STAGE(bufoff, gbase, voff) do { _Pragma("unroll") for (int _i = 0; _i < 2; ++_i) \
;     __builtin_amdgcn_global_load_lds((const unsigned*)((const char*)(gbase) + (voff)[_i]), (PG8_LAS unsigned*)(lds + (bufoff) + ldsw + _i * 8192), 16, 0, 0); } while (0)
; #define PG8_LDA(dst, b, h) do { _Pragma("unroll") for (int m = 0; m < 4; ++m) _Pragma("unroll") for (int k = 0; k < 2; ++k) dst[m][k] = *(const PG8_LAS bf16x8*)(lds + PG8_SA(b, h) + aoff + m * 2048 + k * 1024); } while (0)
; #define PG8_LDB(dst, b, h) do { _Pragma("unroll") for (int n = 0; n < 2; ++n) _Pragma("unroll") for (int k = 0; k < 2; ++k) dst[n][k] = *(const PG8_LAS bf16x8*)(lds + PG8_SB(b, h) + boff + n * 2048 + k * 1024); } while (0)
; #define PG8_BAR __builtin_amdgcn_s_barrier()
; template <class Epi>
; __device__ __forceinline__ void gemm_phase(PG8_LAS unsigned char* lds, const Gemm g, const StaticOrder& S, const Epi& E) {
;     ...
;     for (int t = 0; t < nt; t += 2) {
;       const bool last = (t == nt - 2);
;       const char* a1 = cA + (size_t)(t + 1) * kstep;
;       const char* a2 = last ? nA : cA + (size_t)(t + 2) * kstep; const char* b2 = last ? nB : cB + (size_t)(t + 2) * kstep;
;       const char* a3 = a2 + kstep; const char* b3 = b2 + kstep;
;       PG8_LDB(B0, 0, 0); PG8_SCHED; PG8_LDA(At, 0, 0); PG8_STAGE(PG8_SA(1, 1), a1 + hstep, voffA);
;       PG8_WAIT_L(8); PG8_BAR; PG8_WAIT_L(0); PG8_MMA(0, 0, At, B0); PG8_BAR; PG8_SCHED;
;       PG8_LDB(B1, 0, 1); PG8_STAGE(PG8_SB(0, 0), b2, voffB);
;       PG8_BAR; PG8_WAIT_L(0); PG8_MMA(0, 1, At, B1); PG8_BAR;
;       PG8_LDA(At, 0, 1); PG8_STAGE(PG8_SA(0, 0), a2, voffA);
;       PG8_BAR; PG8_WAIT_L(0); PG8_MMA(1, 0, At, B0); PG8_BAR; PG8_SCHED;
;       PG8_STAGE(PG8_SB(0, 1), b2 + hstep, voffB);
;       PG8_WAIT_V(6); PG8_BAR; PG8_MMA(1, 1, At, B1); PG8_BAR;
;       PG8_LDB(B0, 1, 0); PG8_SCHED; PG8_LDA(At, 1, 0); PG8_STAGE(PG8_SA(0, 1), a2 + hstep, voffA);
;       PG8_WAIT_L(8); PG8_BAR; PG8_WAIT_L(0); PG8_MMA(0, 0, At, B0); PG8_BAR; PG8_SCHED;
;       PG8_LDB(B1, 1, 1); PG8_STAGE(PG8_SB(1, 0), b3, voffB);
;       PG8_BAR; PG8_WAIT_L(0); PG8_MMA(0, 1, At, B1); PG8_BAR;
;       PG8_LDA(At, 1, 1); PG8_STAGE(PG8_SA(1, 0), a3, voffA);
;       PG8_BAR; PG8_WAIT_L(0); PG8_MMA(1, 0, At, B0); PG8_BAR; PG8_SCHED;
;       PG8_STAGE(PG8_SB(1, 1), b3 + hstep, voffB);
;       PG8_WAIT_V(6); PG8_BAR; PG8_MMA(1, 1, At, B1); PG8_BAR;
;     }
	s_add_u32 s60, s46, 0x40000
	s_addc_u32 s61, s47, 0
	s_add_i32 s59, s62, s19
	v_lshl_add_u64 v[156:157], s[60:61], 0, v[148:149]
	s_mov_b32 m0, s59
	s_nop 0
	global_load_lds_dwordx4 v[156:157], off
	v_lshl_add_u64 v[156:157], s[60:61], 0, v[150:151]
	s_add_i32 m0, s59, 0x2000
	s_nop 0
	global_load_lds_dwordx4 v[156:157], off
	s_waitcnt vmcnt(6)
	s_barrier
	s_setprio 1
	v_mfma_f32_16x16x32_bf16 v[54:57], v[228:231], v[196:199], v[54:57]
	v_mfma_f32_16x16x32_bf16 v[50:53], v[236:239], v[196:199], v[50:53]
	v_mfma_f32_16x16x32_bf16 v[38:41], v[228:231], v[204:207], v[38:41]
	v_mfma_f32_16x16x32_bf16 v[34:37], v[236:239], v[204:207], v[34:37]
	v_mfma_f32_16x16x32_bf16 v[22:25], v[228:231], v[212:215], v[22:25]
	v_mfma_f32_16x16x32_bf16 v[18:21], v[236:239], v[212:215], v[18:21]
	v_mfma_f32_16x16x32_bf16 v[6:9], v[228:231], v[220:223], v[6:9]
	v_mfma_f32_16x16x32_bf16 v[2:5], v[236:239], v[220:223], v[2:5]
	v_mfma_f32_16x16x32_bf16 v[54:57], v[232:235], v[200:203], v[54:57]
	v_mfma_f32_16x16x32_bf16 v[50:53], v[240:243], v[200:203], v[50:53]
	v_mfma_f32_16x16x32_bf16 v[38:41], v[232:235], v[208:211], v[38:41]
	v_mfma_f32_16x16x32_bf16 v[34:37], v[240:243], v[208:211], v[34:37]
	v_mfma_f32_16x16x32_bf16 v[22:25], v[232:235], v[216:219], v[22:25]
	v_mfma_f32_16x16x32_bf16 v[18:21], v[240:243], v[216:219], v[18:21]
	v_mfma_f32_16x16x32_bf16 v[6:9], v[232:235], v[224:227], v[6:9]
	v_mfma_f32_16x16x32_bf16 v[2:5], v[240:243], v[224:227], v[2:5]
	s_setprio 0
	s_add_i32 s59, 0, 0x18000
	v_add_u32_e32 v0, s59, v164
	s_barrier
	ds_read_b128 v[156:159], v0
	ds_read_b128 v[160:163], v0 offset:1024
	ds_read_b128 v[188:191], v0 offset:2048
	ds_read_b128 v[192:195], v0 offset:3072
	s_add_u32 s48, s48, 0x40000
	s_addc_u32 s49, s49, 0
	s_mov_b32 m0, s51
	v_lshl_add_u64 v[228:229], s[48:49], 0, v[148:149]
	ds_read_b128 v[196:199], v166 offset:32768
	ds_read_b128 v[200:203], v166 offset:33792
	ds_read_b128 v[204:207], v166 offset:34816
	ds_read_b128 v[208:211], v166 offset:35840
	ds_read_b128 v[212:215], v166 offset:36864
	ds_read_b128 v[216:219], v166 offset:37888
	ds_read_b128 v[220:223], v166 offset:38912
	ds_read_b128 v[224:227], v166 offset:39936
	global_load_lds_dwordx4 v[228:229], off
	v_lshl_add_u64 v[228:229], s[48:49], 0, v[150:151]
	s_mov_b32 m0, s52
	s_nop 0
	global_load_lds_dwordx4 v[228:229], off
	s_waitcnt lgkmcnt(8)
	s_barrier
	s_waitcnt lgkmcnt(0)
	s_setprio 1
	s_waitcnt lgkmcnt(0)
	v_mfma_f32_16x16x32_bf16 v[126:129], v[156:159], v[196:199], v[126:129]
	v_mfma_f32_16x16x32_bf16 v[122:125], v[188:191], v[196:199], v[122:125]
	v_mfma_f32_16x16x32_bf16 v[110:113], v[156:159], v[204:207], v[110:113]
	v_mfma_f32_16x16x32_bf16 v[106:109], v[188:191], v[204:207], v[106:109]
	v_mfma_f32_16x16x32_bf16 v[94:97], v[156:159], v[212:215], v[94:97]
	v_mfma_f32_16x16x32_bf16 v[90:93], v[188:191], v[212:215], v[90:93]
	v_mfma_f32_16x16x32_bf16 v[78:81], v[156:159], v[220:223], v[78:81]
	v_mfma_f32_16x16x32_bf16 v[74:77], v[188:191], v[220:223], v[74:77]
	v_mfma_f32_16x16x32_bf16 v[126:129], v[160:163], v[200:203], v[126:129]
	v_mfma_f32_16x16x32_bf16 v[122:125], v[192:195], v[200:203], v[122:125]
	v_mfma_f32_16x16x32_bf16 v[110:113], v[160:163], v[208:211], v[110:113]
	v_mfma_f32_16x16x32_bf16 v[106:109], v[192:195], v[208:211], v[106:109]
	v_mfma_f32_16x16x32_bf16 v[94:97], v[160:163], v[216:219], v[94:97]
	v_mfma_f32_16x16x32_bf16 v[90:93], v[192:195], v[216:219], v[90:93]
	v_mfma_f32_16x16x32_bf16 v[78:81], v[160:163], v[224:227], v[78:81]
	v_mfma_f32_16x16x32_bf16 v[74:77], v[192:195], v[224:227], v[74:77]
	s_setprio 0
	s_barrier
	s_add_i32 s48, 0, 0x1c000
	s_add_i32 s49, s59, s19
	v_add_u32_e32 v0, s48, v164
	v_lshl_add_u64 v[244:245], v[244:245], 0, s[4:5]
	s_mov_b32 m0, s49
	ds_read_b128 v[228:231], v0
	ds_read_b128 v[232:235], v0 offset:1024
	ds_read_b128 v[236:239], v0 offset:2048
	ds_read_b128 v[240:243], v0 offset:3072
	global_load_lds_dwordx4 v[244:245], off
	v_lshl_add_u64 v[244:245], v[246:247], 0, s[4:5]
	s_add_i32 m0, s49, 0x2000
	s_nop 0
	global_load_lds_dwordx4 v[244:245], off
	s_barrier
	s_waitcnt lgkmcnt(0)
	s_setprio 1
	s_waitcnt lgkmcnt(0)
	v_mfma_f32_16x16x32_bf16 v[118:121], v[228:231], v[196:199], v[118:121]
	v_mfma_f32_16x16x32_bf16 v[114:117], v[236:239], v[196:199], v[114:117]
	v_mfma_f32_16x16x32_bf16 v[102:105], v[228:231], v[204:207], v[102:105]
	v_mfma_f32_16x16x32_bf16 v[98:101], v[236:239], v[204:207], v[98:101]
	v_mfma_f32_16x16x32_bf16 v[86:89], v[228:231], v[212:215], v[86:89]
	v_mfma_f32_16x16x32_bf16 v[82:85], v[236:239], v[212:215], v[82:85]
	v_mfma_f32_16x16x32_bf16 v[70:73], v[228:231], v[220:223], v[70:73]
	v_mfma_f32_16x16x32_bf16 v[66:69], v[236:239], v[220:223], v[66:69]
	v_mfma_f32_16x16x32_bf16 v[118:121], v[232:235], v[200:203], v[118:121]
	v_mfma_f32_16x16x32_bf16 v[114:117], v[240:243], v[200:203], v[114:117]
	v_mfma_f32_16x16x32_bf16 v[102:105], v[232:235], v[208:211], v[102:105]
	v_mfma_f32_16x16x32_bf16 v[98:101], v[240:243], v[208:211], v[98:101]
	v_mfma_f32_16x16x32_bf16 v[86:89], v[232:235], v[216:219], v[86:89]
	v_mfma_f32_16x16x32_bf16 v[82:85], v[240:243], v[216:219], v[82:85]
	v_mfma_f32_16x16x32_bf16 v[70:73], v[232:235], v[224:227], v[70:73]
	v_mfma_f32_16x16x32_bf16 v[66:69], v[240:243], v[224:227], v[66:69]
	s_setprio 0
	s_mov_b32 m0, s53
	v_lshl_add_u64 v[244:245], v[248:249], 0, s[4:5]
	s_barrier
	ds_read_b128 v[196:199], v166 offset:49152
	ds_read_b128 v[200:203], v166 offset:50176
	ds_read_b128 v[204:207], v166 offset:51200
	ds_read_b128 v[208:211], v166 offset:52224
	ds_read_b128 v[212:215], v166 offset:53248
	ds_read_b128 v[216:219], v166 offset:54272
	ds_read_b128 v[220:223], v166 offset:55296
	ds_read_b128 v[224:227], v166 offset:56320
	global_load_lds_dwordx4 v[244:245], off
	v_lshl_add_u64 v[178:179], v[178:179], 0, s[4:5]
	s_mov_b32 m0, s54
	s_nop 0
	global_load_lds_dwordx4 v[178:179], off
	s_barrier
; #define PG8_STAGE(bufoff, gbase, voff) do { _Pragma("unroll") for (int _i = 0; _i < 2; ++_i) \
;     __builtin_amdgcn_global_load_lds((const unsigned*)((const char*)(gbase) + (voff)[_i]), (PG8_LAS unsigned*)(lds + (bufoff) + ldsw + _i * 8192), 16, 0, 0); } while (0)
; #define PG8_LDA(dst, b, h) do { _Pragma("unroll") for (int m = 0; m < 4; ++m) _Pragma("unroll") for (int k = 0; k < 2; ++k) dst[m][k] = *(const PG8_LAS bf16x8*)(lds + PG8_SA(b, h) + aoff + m * 2048 + k * 1024); } while (0)
; #define PG8_LDB(dst, b, h) do { _Pragma("unroll") for (int n = 0; n < 2; ++n) _Pragma("unroll") for (int k = 0; k < 2; ++k) dst[n][k] = *(const PG8_LAS bf16x8*)(lds + PG8_SB(b, h) + boff + n * 2048 + k * 1024); } while (0)
; #define PG8_BAR __builtin_amdgcn_s_barrier()
; template <class Epi>
; __device__ __forceinline__ void gemm_phase(PG8_LAS unsigned char* lds, const Gemm g, const StaticOrder& S, const Epi& E) {
;     ...
;     for (int t = 0; t < nt; t += 2) {
;       const bool last = (t == nt - 2);
;       const char* a1 = cA + (size_t)(t + 1) * kstep;
;       const char* a2 = last ? nA : cA + (size_t)(t + 2) * kstep; const char* b2 = last ? nB : cB + (size_t)(t + 2) * kstep;
;       const char* a3 = a2 + kstep; const char* b3 = b2 + kstep;
;       PG8_LDB(B0, 0, 0); PG8_SCHED; PG8_LDA(At, 0, 0); PG8_STAGE(PG8_SA(1, 1), a1 + hstep, voffA);
;       PG8_WAIT_L(8); PG8_BAR; PG8_WAIT_L(0); PG8_MMA(0, 0, At, B0); PG8_BAR; PG8_SCHED;
;       PG8_LDB(B1, 0, 1); PG8_STAGE(PG8_SB(0, 0), b2, voffB);
;       PG8_BAR; PG8_WAIT_L(0); PG8_MMA(0, 1, At, B1); PG8_BAR;
;       PG8_LDA(At, 0, 1); PG8_STAGE(PG8_SA(0, 0), a2, voffA);
;       PG8_BAR; PG8_WAIT_L(0); PG8_MMA(1, 0, At, B0); PG8_BAR; PG8_SCHED;
;       PG8_STAGE(PG8_SB(0, 1), b2 + hstep, voffB);
;       PG8_WAIT_V(6); PG8_BAR; PG8_MMA(1, 1, At, B1); PG8_BAR;
;       PG8_LDB(B0, 1, 0); PG8_SCHED; PG8_LDA(At, 1, 0); PG8_STAGE(PG8_SA(0, 1), a2 + hstep, voffA);
;       PG8_WAIT_L(8); PG8_BAR; PG8_WAIT_L(0); PG8_MMA(0, 0, At, B0); PG8_BAR; PG8_SCHED;
;       PG8_LDB(B1, 1, 1); PG8_STAGE(PG8_SB(1, 0), b3, voffB);
;       PG8_BAR; PG8_WAIT_L(0); PG8_MMA(0, 1, At, B1); PG8_BAR;
;       PG8_LDA(At, 1, 1); PG8_STAGE(PG8_SA(1, 0), a3, voffA);
;       PG8_BAR; PG8_WAIT_L(0); PG8_MMA(1, 0, At, B0); PG8_BAR; PG8_SCHED;
;       PG8_STAGE(PG8_SB(1, 1), b3 + hstep, voffB);
;       PG8_WAIT_V(6); PG8_BAR; PG8_MMA(1, 1, At, B1); PG8_BAR;
;     }
	s_waitcnt lgkmcnt(0)
	s_setprio 1
	s_waitcnt lgkmcnt(0)
	v_mfma_f32_16x16x32_bf16 v[62:65], v[156:159], v[196:199], v[62:65]
	v_mfma_f32_16x16x32_bf16 v[58:61], v[188:191], v[196:199], v[58:61]
	v_mfma_f32_16x16x32_bf16 v[46:49], v[156:159], v[204:207], v[46:49]
	v_mfma_f32_16x16x32_bf16 v[42:45], v[188:191], v[204:207], v[42:45]
	v_mfma_f32_16x16x32_bf16 v[30:33], v[156:159], v[212:215], v[30:33]
	v_mfma_f32_16x16x32_bf16 v[26:29], v[188:191], v[212:215], v[26:29]
	v_mfma_f32_16x16x32_bf16 v[14:17], v[156:159], v[220:223], v[14:17]
	v_mfma_f32_16x16x32_bf16 v[10:13], v[188:191], v[220:223], v[10:13]
	v_mfma_f32_16x16x32_bf16 v[62:65], v[160:163], v[200:203], v[62:65]
	v_mfma_f32_16x16x32_bf16 v[58:61], v[192:195], v[200:203], v[58:61]
	v_mfma_f32_16x16x32_bf16 v[46:49], v[160:163], v[208:211], v[46:49]
	v_mfma_f32_16x16x32_bf16 v[42:45], v[192:195], v[208:211], v[42:45]
	v_mfma_f32_16x16x32_bf16 v[30:33], v[160:163], v[216:219], v[30:33]
	v_mfma_f32_16x16x32_bf16 v[26:29], v[192:195], v[216:219], v[26:29]
	v_mfma_f32_16x16x32_bf16 v[14:17], v[160:163], v[224:227], v[14:17]
	v_mfma_f32_16x16x32_bf16 v[10:13], v[192:195], v[224:227], v[10:13]
	s_setprio 0
	s_barrier
	s_add_u32 s46, s46, 0x40080
	s_addc_u32 s47, s47, 0
	s_add_i32 s48, s48, s19
	v_lshl_add_u64 v[156:157], s[46:47], 0, v[148:149]
	s_mov_b32 m0, s48
	s_nop 0
	global_load_lds_dwordx4 v[156:157], off
	v_lshl_add_u64 v[156:157], s[46:47], 0, v[150:151]
	s_add_i32 m0, s48, 0x2000
	s_nop 0
	global_load_lds_dwordx4 v[156:157], off
	s_waitcnt vmcnt(6)
	s_barrier
	s_setprio 1
	v_mfma_f32_16x16x32_bf16 v[54:57], v[228:231], v[196:199], v[54:57]
	v_mfma_f32_16x16x32_bf16 v[50:53], v[236:239], v[196:199], v[50:53]
	v_mfma_f32_16x16x32_bf16 v[38:41], v[228:231], v[204:207], v[38:41]
	v_mfma_f32_16x16x32_bf16 v[34:37], v[236:239], v[204:207], v[34:37]
	v_mfma_f32_16x16x32_bf16 v[22:25], v[228:231], v[212:215], v[22:25]
	v_mfma_f32_16x16x32_bf16 v[18:21], v[236:239], v[212:215], v[18:21]
	v_mfma_f32_16x16x32_bf16 v[6:9], v[228:231], v[220:223], v[6:9]
	v_mfma_f32_16x16x32_bf16 v[2:5], v[236:239], v[220:223], v[2:5]
	v_mfma_f32_16x16x32_bf16 v[54:57], v[232:235], v[200:203], v[54:57]
	v_mfma_f32_16x16x32_bf16 v[50:53], v[240:243], v[200:203], v[50:53]
	v_mfma_f32_16x16x32_bf16 v[38:41], v[232:235], v[208:211], v[38:41]
	v_mfma_f32_16x16x32_bf16 v[34:37], v[240:243], v[208:211], v[34:37]
	v_mfma_f32_16x16x32_bf16 v[22:25], v[232:235], v[216:219], v[22:25]
	v_mfma_f32_16x16x32_bf16 v[18:21], v[240:243], v[216:219], v[18:21]
	v_mfma_f32_16x16x32_bf16 v[6:9], v[232:235], v[224:227], v[6:9]
	v_mfma_f32_16x16x32_bf16 v[2:5], v[240:243], v[224:227], v[2:5]
	s_setprio 0
	s_add_i32 s58, s58, 2
	s_add_u32 s44, s44, 0x100
	s_addc_u32 s45, s45, 0
	s_add_u32 s56, s56, 0x100
	s_addc_u32 s57, s57, 0
	s_cmp_gt_u32 s58, 13
	s_barrier
	s_cbranch_scc0 .LBB0_1593
;   __device__ __forceinline__ void operator()(const f32x4 (&acc)[2][2][4][2], const pg8::Unit& u, int wr, int wc, int fr, int fq) const {
; #pragma unroll
;     for (int ai = 0; ai < 2; ++ai)
; #pragma unroll
;       for (int m = 0; m < 4; ++m) { const int row = u.pm * 256 + ai * 128 + wr * 64 + m * 16 + fr;
; #pragma unroll
;         for (int bj = 0; bj < 2; ++bj)
; #pragma unroll
;           for (int n = 0; n < 2; ++n) f(row, u.pn * 256 + bj * 128 + wc * 32 + n * 16 + 4 * fq, acc[ai][bj][m][n]); }
;   }
	s_movk_i32 s7, 0xa00
	v_bfe_u32 v228, v168, 4, 1
	v_mul_u32_u24_e32 v228, 24, v228
	v_lshl_add_u32 v228, v165, 1, v228
	v_mad_u32_u24 v228, v147, s7, v228
	s_mul_i32 s44, s42, 0xa0000
	s_lshl_b32 s46, s30, 9
	s_add_i32 s44, s44, s46
	s_cmp_lt_u32 s30, 5
	s_cselect_b32 s46, s2, s26
	s_cselect_b32 s47, s3, s27
	s_cselect_b32 s48, 0, 0xa00
	s_sub_u32 s44, s44, s48
	s_add_u32 s44, s46, s44
	s_addc_u32 s45, s47, 0
	v_cvt_pk_bf16_f32 v125, v124, v125
	v_cvt_pk_bf16_f32 v124, v122, v123
	v_cvt_pk_bf16_f32 v122, v126, v127
	v_cvt_pk_bf16_f32 v123, v128, v129
	v_cvt_pk_bf16_f32 v117, v116, v117
	v_cvt_pk_bf16_f32 v116, v114, v115
	v_cvt_pk_bf16_f32 v114, v118, v119
	v_cvt_pk_bf16_f32 v115, v120, v121
	v_permlane16_swap_b32_e32 v122, v124
	v_permlane16_swap_b32_e32 v123, v125
	v_permlane16_swap_b32_e32 v114, v116
	v_permlane16_swap_b32_e32 v115, v117
	global_store_dwordx4 v228, v[122:125], s[44:45]
	global_store_dwordx4 v228, v[114:117], s[44:45] offset:256
	s_add_u32 s44, s44, 0xa000
	s_addc_u32 s45, s45, 0
	v_cvt_pk_bf16_f32 v109, v108, v109
	v_cvt_pk_bf16_f32 v108, v106, v107
	v_cvt_pk_bf16_f32 v106, v110, v111
	v_cvt_pk_bf16_f32 v107, v112, v113
	v_cvt_pk_bf16_f32 v101, v100, v101
	v_cvt_pk_bf16_f32 v100, v98, v99
	v_cvt_pk_bf16_f32 v98, v102, v103
	v_cvt_pk_bf16_f32 v99, v104, v105
	v_permlane16_swap_b32_e32 v106, v108
	v_permlane16_swap_b32_e32 v107, v109
	v_permlane16_swap_b32_e32 v98, v100
	v_permlane16_swap_b32_e32 v99, v101
	global_store_dwordx4 v228, v[106:109], s[44:45]
	global_store_dwordx4 v228, v[98:101], s[44:45] offset:256
	s_add_u32 s44, s44, 0xa000
	s_addc_u32 s45, s45, 0
	v_cvt_pk_bf16_f32 v93, v92, v93
	v_cvt_pk_bf16_f32 v92, v90, v91
	v_cvt_pk_bf16_f32 v90, v94, v95
	v_cvt_pk_bf16_f32 v91, v96, v97
	v_cvt_pk_bf16_f32 v85, v84, v85
	v_cvt_pk_bf16_f32 v84, v82, v83
	v_cvt_pk_bf16_f32 v82, v86, v87
	v_cvt_pk_bf16_f32 v83, v88, v89
	v_permlane16_swap_b32_e32 v90, v92
	v_permlane16_swap_b32_e32 v91, v93
	v_permlane16_swap_b32_e32 v82, v84
	v_permlane16_swap_b32_e32 v83, v85
	global_store_dwordx4 v228, v[90:93], s[44:45]
	global_store_dwordx4 v228, v[82:85], s[44:45] offset:256
	s_add_u32 s44, s44, 0xa000
	s_addc_u32 s45, s45, 0
	v_cvt_pk_bf16_f32 v77, v76, v77
	v_cvt_pk_bf16_f32 v76, v74, v75
	v_cvt_pk_bf16_f32 v74, v78, v79
	v_cvt_pk_bf16_f32 v75, v80, v81
	v_cvt_pk_bf16_f32 v69, v68, v69
	v_cvt_pk_bf16_f32 v68, v66, v67
	v_cvt_pk_bf16_f32 v66, v70, v71
	v_cvt_pk_bf16_f32 v67, v72, v73
	v_permlane16_swap_b32_e32 v74, v76
	v_permlane16_swap_b32_e32 v75, v77
	v_permlane16_swap_b32_e32 v66, v68
	v_permlane16_swap_b32_e32 v67, v69
	global_store_dwordx4 v228, v[74:77], s[44:45]
	global_store_dwordx4 v228, v[66:69], s[44:45] offset:256
	s_add_u32 s44, s44, 0x32000
	s_addc_u32 s45, s45, 0
	v_cvt_pk_bf16_f32 v61, v60, v61
	v_cvt_pk_bf16_f32 v60, v58, v59
	v_cvt_pk_bf16_f32 v58, v62, v63
	v_cvt_pk_bf16_f32 v59, v64, v65
	v_cvt_pk_bf16_f32 v53, v52, v53
	v_cvt_pk_bf16_f32 v52, v50, v51
	v_cvt_pk_bf16_f32 v50, v54, v55
	v_cvt_pk_bf16_f32 v51, v56, v57
	v_permlane16_swap_b32_e32 v58, v60
	v_permlane16_swap_b32_e32 v59, v61
	v_permlane16_swap_b32_e32 v50, v52
	v_permlane16_swap_b32_e32 v51, v53
	global_store_dwordx4 v228, v[58:61], s[44:45]
	global_store_dwordx4 v228, v[50:53], s[44:45] offset:256
	s_add_u32 s44, s44, 0xa000
	s_addc_u32 s45, s45, 0
	v_cvt_pk_bf16_f32 v45, v44, v45
	v_cvt_pk_bf16_f32 v44, v42, v43
	v_cvt_pk_bf16_f32 v42, v46, v47
	v_cvt_pk_bf16_f32 v43, v48, v49
	v_cvt_pk_bf16_f32 v37, v36, v37
	v_cvt_pk_bf16_f32 v36, v34, v35
	v_cvt_pk_bf16_f32 v34, v38, v39
	v_cvt_pk_bf16_f32 v35, v40, v41
	v_permlane16_swap_b32_e32 v42, v44
	v_permlane16_swap_b32_e32 v43, v45
	v_permlane16_swap_b32_e32 v34, v36
	v_permlane16_swap_b32_e32 v35, v37
	global_store_dwordx4 v228, v[42:45], s[44:45]
	global_store_dwordx4 v228, v[34:37], s[44:45] offset:256
	s_add_u32 s44, s44, 0xa000
	s_addc_u32 s45, s45, 0
	v_cvt_pk_bf16_f32 v29, v28, v29
	v_cvt_pk_bf16_f32 v28, v26, v27
	v_cvt_pk_bf16_f32 v26, v30, v31
	v_cvt_pk_bf16_f32 v27, v32, v33
	v_cvt_pk_bf16_f32 v21, v20, v21
	v_cvt_pk_bf16_f32 v20, v18, v19
	v_cvt_pk_bf16_f32 v18, v22, v23
	v_cvt_pk_bf16_f32 v19, v24, v25
	v_permlane16_swap_b32_e32 v26, v28
	v_permlane16_swap_b32_e32 v27, v29
	v_permlane16_swap_b32_e32 v18, v20
	v_permlane16_swap_b32_e32 v19, v21
	global_store_dwordx4 v228, v[26:29], s[44:45]
	global_store_dwordx4 v228, v[18:21], s[44:45] offset:256
	s_add_u32 s44, s44, 0xa000
	s_addc_u32 s45, s45, 0
	v_cvt_pk_bf16_f32 v13, v12, v13
	v_cvt_pk_bf16_f32 v12, v10, v11
	v_cvt_pk_bf16_f32 v10, v14, v15
	v_cvt_pk_bf16_f32 v11, v16, v17
	v_cvt_pk_bf16_f32 v5, v4, v5
	v_cvt_pk_bf16_f32 v4, v2, v3
	v_cvt_pk_bf16_f32 v2, v6, v7
	v_cvt_pk_bf16_f32 v3, v8, v9
	v_permlane16_swap_b32_e32 v10, v12
	v_permlane16_swap_b32_e32 v11, v13
	v_permlane16_swap_b32_e32 v2, v4
	v_permlane16_swap_b32_e32 v3, v5
	global_store_dwordx4 v228, v[10:13], s[44:45]
	global_store_dwordx4 v228, v[2:5], s[44:45] offset:256
	s_branch .Llin_latch

; __global__ void __launch_bounds__(512, 2) mega_kernel(P p) {
;   cg::grid_group grid = cg::this_grid();
;   volatile __attribute__((address_space(3))) unsigned* st = (volatile __attribute__((address_space(3))) unsigned*)(dyn_smem + 131072);
;   if (threadIdx.x < 4) st[threadIdx.x] = 0u;
;   __syncthreads();
;   const XcdBarrier xb = xcd_barrier_post(p.bar, st);
;   for (int si = 0; si < p.nsched; si++) {
;     run_phase(p, p.sched[si * 3], p.sched[si * 3 + 1], p.sched[si * 3 + 2], dyn_smem);
;     if (si + 1 < p.nsched) { if (p.pad_ != 0) grid.sync(); xcd_barrier(xb); }
;   }
; }
	.amdhsa_kernel _Z11mega_kernel1P
		.amdhsa_group_segment_fixed_size 0
		.amdhsa_private_segment_fixed_size 0
		.amdhsa_kernarg_size 1360
		.amdhsa_user_sgpr_count 2
		.amdhsa_user_sgpr_dispatch_ptr 0
		.amdhsa_user_sgpr_queue_ptr 0
		.amdhsa_user_sgpr_kernarg_segment_ptr 1
		.amdhsa_user_sgpr_dispatch_id 0
		.amdhsa_user_sgpr_kernarg_preload_length 0
		.amdhsa_user_sgpr_kernarg_preload_offset 0
		.amdhsa_user_sgpr_private_segment_size 0
		.amdhsa_uses_dynamic_stack 0
		.amdhsa_enable_private_segment 0
		.amdhsa_system_sgpr_workgroup_id_x 1
		.amdhsa_system_sgpr_workgroup_id_y 0
		.amdhsa_system_sgpr_workgroup_id_z 0
		.amdhsa_system_sgpr_workgroup_info 0
		.amdhsa_system_vgpr_workitem_id 2
		.amdhsa_next_free_vgpr 256
		.amdhsa_next_free_sgpr 102
		.amdhsa_accum_offset 256
		.amdhsa_reserve_vcc 1
		.amdhsa_float_round_mode_32 0
		.amdhsa_float_round_mode_16_64 0
		.amdhsa_float_denorm_mode_32 3
		.amdhsa_float_denorm_mode_16_64 3
		.amdhsa_dx10_clamp 1
		.amdhsa_ieee_mode 1
		.amdhsa_fp16_overflow 0
		.amdhsa_tg_split 0
		.amdhsa_exception_fp_ieee_invalid_op 0
		.amdhsa_exception_fp_denorm_src 0
		.amdhsa_exception_fp_ieee_div_zero 0
		.amdhsa_exception_fp_ieee_overflow 0
		.amdhsa_exception_fp_ieee_underflow 0
		.amdhsa_exception_fp_ieee_inexact 0
		.amdhsa_exception_int_div_zero 0
	.end_amdhsa_kernel

; __global__ void __launch_bounds__(512, 2) mega_kernel(P p) {
;   cg::grid_group grid = cg::this_grid();
;   volatile __attribute__((address_space(3))) unsigned* st = (volatile __attribute__((address_space(3))) unsigned*)(dyn_smem + 131072);
;   if (threadIdx.x < 4) st[threadIdx.x] = 0u;
;   __syncthreads();
;   const XcdBarrier xb = xcd_barrier_post(p.bar, st);
;   for (int si = 0; si < p.nsched; si++) {
;     run_phase(p, p.sched[si * 3], p.sched[si * 3 + 1], p.sched[si * 3 + 2], dyn_smem);
;     if (si + 1 < p.nsched) { if (p.pad_ != 0) grid.sync(); xcd_barrier(xb); }
;   }
; }
amdhsa.kernels:
  - .agpr_count:     0
    .args:
      - .offset:         0
        .size:           1104
        .value_kind:     by_value
      - .offset:         1104
        .size:           4
        .value_kind:     hidden_block_count_x
      - .offset:         1108
        .size:           4
        .value_kind:     hidden_block_count_y
      - .offset:         1112
        .size:           4
        .value_kind:     hidden_block_count_z
      - .offset:         1116
        .size:           2
        .value_kind:     hidden_group_size_x
      - .offset:         1118
        .size:           2
        .value_kind:     hidden_group_size_y
      - .offset:         1120
        .size:           2
        .value_kind:     hidden_group_size_z
      - .offset:         1122
        .size:           2
        .value_kind:     hidden_remainder_x
      - .offset:         1124
        .size:           2
        .value_kind:     hidden_remainder_y
      - .offset:         1126
        .size:           2
        .value_kind:     hidden_remainder_z
      - .offset:         1144
        .size:           8
        .value_kind:     hidden_global_offset_x
      - .offset:         1152
        .size:           8
        .value_kind:     hidden_global_offset_y
      - .offset:         1160
        .size:           8
        .value_kind:     hidden_global_offset_z
      - .offset:         1168
        .size:           2
        .value_kind:     hidden_grid_dims
      - .offset:         1192
        .size:           8
        .value_kind:     hidden_multigrid_sync_arg
      - .offset:         1224
        .size:           4
        .value_kind:     hidden_dynamic_lds_size
    .group_segment_fixed_size: 0
    .kernarg_segment_align: 8
    .kernarg_segment_size: 1360
    .language:       OpenCL C
    .language_version:
      - 2
      - 0
    .max_flat_workgroup_size: 512
    .name:           _Z11mega_kernel1P
    .private_segment_fixed_size: 0
    .sgpr_count:     108
    .sgpr_spill_count: 272
    .symbol:         _Z11mega_kernel1P.kd
    .uniform_work_group_size: 1
    .uses_dynamic_stack: false
    .vgpr_count:     256
    .vgpr_spill_count: 0
    .wavefront_size: 64
